# removed 4 conservative compiler vmcnt(0) waits in GEMM tile prologues (EPI1 mid-DMA-issue, EPI2 after first barrier, EPI4 both variants after DMA issue) so the K loop starts when stage 0 lands
# baseline (speedup 1.0000x reference)
.LBB0_203:
	s_and_b32 s4, s69, 7
	s_mulk_i32 s4, 0x60
	s_ashr_i32 s5, s69, 3
	s_add_i32 s4, s4, s5
	s_mul_hi_i32 s5, s4, 0x2aaaaaab
	s_lshr_b32 s6, s5, 31
	s_add_i32 s5, s5, s6
	s_mul_i32 s6, s5, 6
	v_mov_b32_e32 v131, v157
	s_sub_i32 s7, s4, s6
	s_lshl_b32 s31, s5, 8
	v_readfirstlane_b32 s4, v131
	s_ashr_i32 s5, s4, 1
	s_and_b32 s5, s5, 0xffffff80
	v_and_b32_e32 v133, 15, v131
	s_add_i32 s6, s31, s5
	v_or_b32_e32 v144, s6, v133
	v_ashrrev_i32_e32 v145, 31, v144
	v_lshl_add_u64 v[0:1], v[144:145], 2, s[38:39]
	s_waitcnt vmcnt(0)
	v_mov_b32_e32 v10, v157
	global_load_dword v146, v[0:1], off
	global_load_dword v142, v[0:1], off offset:64
	global_load_dword v140, v[0:1], off offset:128
	global_load_dword v138, v[0:1], off offset:192
	global_load_dword v136, v[0:1], off offset:256
	global_load_dword v134, v[0:1], off offset:320
	global_load_dword v132, v[0:1], off offset:384
	global_load_dword v130, v[0:1], off offset:448
	s_lshl_b32 s5, s7, 8
	v_readfirstlane_b32 s74, v10
	s_ashr_i32 s7, s74, 6
	s_lshl_b32 s72, s7, 2
	s_add_i32 s75, s5, 0xffffff00
	s_cmp_lt_i32 s7, 4
	s_cselect_b64 s[8:9], -1, 0
	s_and_b32 s78, s74, 0xffffffc0
	s_and_b64 s[10:11], s[8:9], exec
	s_cselect_b32 s10, s31, s75
	s_add_i32 s10, s10, s78
	s_and_b64 s[8:9], s[8:9], exec
	s_cselect_b32 s18, s53, s68
	s_cselect_b32 s19, s52, s14
	s_ashr_i32 s11, s10, 31
	s_lshl_b64 s[8:9], s[10:11], 11
	s_add_u32 s8, s19, s8
	s_addc_u32 s9, s18, s9
	s_or_b32 s18, s72, 1
	s_cmp_lt_i32 s18, 16
	s_cselect_b64 s[10:11], -1, 0
	s_lshl_b32 s70, s18, 4
	s_and_b64 s[18:19], s[10:11], exec
	s_cselect_b32 s79, s31, s75
	s_add_i32 s18, s79, s70
	s_and_b64 s[10:11], s[10:11], exec
	s_cselect_b32 s84, s53, s68
	s_cselect_b32 s85, s52, s14
	s_ashr_i32 s19, s18, 31
	s_lshl_b64 s[10:11], s[18:19], 11
	s_add_u32 s10, s85, s10
	s_addc_u32 s11, s84, s11
	s_or_b32 s70, s72, 2
	s_cmp_lt_i32 s70, 16
	s_cselect_b64 s[18:19], -1, 0
	s_lshl_b32 s73, s70, 4
	s_and_b64 s[70:71], s[18:19], exec
	s_cselect_b32 s86, s31, s75
	s_add_i32 s70, s86, s73
	s_and_b64 s[18:19], s[18:19], exec
	s_cselect_b32 s87, s53, s68
	s_cselect_b32 vcc_lo, s52, s14
	s_ashr_i32 s71, s70, 31
	s_lshl_b64 s[18:19], s[70:71], 11
	s_add_u32 s18, vcc_lo, s18
	s_addc_u32 s19, s87, s19
	s_or_b32 s72, s72, 3
	s_cmp_lt_i32 s72, 16
	s_cselect_b64 s[70:71], -1, 0
	s_lshl_b32 vcc_hi, s72, 4
	s_and_b64 s[72:73], s[70:71], exec
	s_cselect_b32 s31, s31, s75
	s_add_i32 s72, s31, vcc_hi
	s_and_b64 s[70:71], s[70:71], exec
	v_lshrrev_b32_e32 v11, 4, v10
	s_cselect_b32 s75, s53, s68
	s_cselect_b32 vcc_hi, s52, s14
	s_ashr_i32 s73, s72, 31
	v_sub_u32_e32 v1, 0, v11
	s_lshl_b64 s[70:71], s[72:73], 11
	v_lshlrev_b32_e32 v0, 9, v10
	v_xor_b32_e32 v1, v10, v1
	s_add_u32 s70, vcc_hi, s70
	v_and_b32_e32 v0, 0x7800, v0
	v_lshlrev_b32_e32 v1, 4, v1
	s_addc_u32 s71, s75, s71
	s_lshl_b32 s7, s7, 12
	v_and_or_b32 v112, v1, 48, v0
	s_mov_b32 m0, s7
	v_lshl_add_u64 v[0:1], s[8:9], 0, v[112:113]
	global_load_lds_dwordx4 v112, s[8:9]
	s_or_b32 m0, s7, 0x400
	v_lshl_add_u64 v[2:3], s[10:11], 0, v[112:113]
	global_load_lds_dwordx4 v112, s[10:11]
	s_or_b32 m0, s7, 0x800
	v_lshl_add_u64 v[8:9], v[0:1], 0, 64
	global_load_lds_dwordx4 v112, s[18:19]
	s_or_b32 m0, s7, 0xc00
	v_lshl_add_u64 v[4:5], s[18:19], 0, v[112:113]
	global_load_lds_dwordx4 v112, s[70:71]
	s_add_i32 m0, s7, 0x8000
	v_lshl_add_u64 v[6:7], s[70:71], 0, v[112:113]
	global_load_lds_dwordx4 v[8:9], off
	v_lshl_add_u64 v[8:9], v[2:3], 0, 64
	s_add_i32 m0, s7, 0x8400
	v_lshl_add_u64 v[2:3], v[2:3], 0, s[90:91]
	global_load_lds_dwordx4 v[8:9], off
	v_lshl_add_u64 v[8:9], v[4:5], 0, 64
	s_add_i32 m0, s7, 0x8800
	s_lshr_b32 s8, s74, 1
	global_load_lds_dwordx4 v[8:9], off
	v_lshl_add_u64 v[8:9], v[6:7], 0, 64
	s_add_i32 m0, s7, 0x8c00
	v_and_b32_e32 v12, 15, v10
	global_load_lds_dwordx4 v[8:9], off
	s_add_i32 m0, s7, 0x10000
	v_lshl_add_u64 v[8:9], v[0:1], 0, s[90:91]
	global_load_lds_dwordx4 v[8:9], off
	s_add_i32 m0, s7, 0x10400
	s_and_b32 s8, s8, 0x3ffff80
	global_load_lds_dwordx4 v[2:3], off
	v_lshl_add_u64 v[2:3], v[4:5], 0, s[90:91]
	s_add_i32 m0, s7, 0x10800
	v_lshl_add_u64 v[154:155], v[0:1], 0, s[76:77]
	global_load_lds_dwordx4 v[2:3], off
	v_lshl_add_u64 v[2:3], v[6:7], 0, s[90:91]
	s_add_i32 m0, s7, 0x10c00
	v_mov_b32_e32 v0, 0
	global_load_lds_dwordx4 v[2:3], off
	v_lshrrev_b32_e32 v2, 2, v10
	v_sub_u32_e32 v2, 0, v2
	v_bitop3_b32 v2, v11, 3, v2 bitop3:0x48
	v_or_b32_e32 v3, s8, v12
	v_lshlrev_b32_e32 v2, 4, v2
	s_and_b32 s8, s74, 0xc0
	v_lshl_or_b32 v135, v3, 6, v2
	v_or_b32_e32 v3, s8, v12
	s_add_i32 s8, s31, s78
	s_ashr_i32 s9, s8, 31
	s_lshl_b64 s[8:9], s[8:9], 11
	s_add_u32 s8, vcc_hi, s8
	v_lshlrev_b32_e32 v3, 6, v3
	s_addc_u32 s9, s75, s9
	v_or3_b32 v137, v2, v3, s83
	v_lshl_add_u64 v[2:3], s[8:9], 0, v[112:113]
	s_add_i32 s8, s86, s78
	s_ashr_i32 s9, s8, 31
	s_lshl_b64 s[8:9], s[8:9], 11
	s_add_u32 s8, vcc_lo, s8
	s_addc_u32 s9, s87, s9
	v_lshl_add_u64 v[148:149], v[2:3], 0, s[92:93]
	v_lshl_add_u64 v[2:3], s[8:9], 0, v[112:113]
	s_add_i32 s8, s79, s78
	s_ashr_i32 s9, s8, 31
	s_lshl_b64 s[8:9], s[8:9], 11
	s_add_u32 s8, s85, s8
	s_addc_u32 s9, s84, s9
	v_lshl_add_u64 v[150:151], v[2:3], 0, s[94:95]
	v_lshl_add_u64 v[2:3], s[8:9], 0, v[112:113]
	v_lshl_add_u64 v[152:153], v[2:3], 0, s[96:97]
	s_mov_b32 s8, 0x18000
	v_mov_b32_e32 v1, v0
	v_mov_b32_e32 v2, v0
	v_mov_b32_e32 v3, v0
	v_mov_b32_e32 v4, v0
	v_mov_b32_e32 v5, v0
	v_mov_b32_e32 v6, v0
	v_mov_b32_e32 v7, v0
	v_mov_b32_e32 v8, v0
	v_mov_b32_e32 v9, v0
	v_mov_b32_e32 v10, v0
	v_mov_b32_e32 v11, v0
	v_mov_b32_e32 v12, v0
	v_mov_b32_e32 v13, v0
	v_mov_b32_e32 v14, v0
	v_mov_b32_e32 v15, v0
	v_mov_b32_e32 v16, v0
	v_mov_b32_e32 v17, v0
	v_mov_b32_e32 v18, v0
	v_mov_b32_e32 v19, v0
	v_mov_b32_e32 v20, v0
	v_mov_b32_e32 v21, v0
	v_mov_b32_e32 v22, v0
	v_mov_b32_e32 v23, v0
	v_mov_b32_e32 v24, v0
	v_mov_b32_e32 v25, v0
	v_mov_b32_e32 v26, v0
	v_mov_b32_e32 v27, v0
	v_mov_b32_e32 v28, v0
	v_mov_b32_e32 v29, v0
	v_mov_b32_e32 v30, v0
	v_mov_b32_e32 v31, v0
	v_mov_b32_e32 v32, v0
	v_mov_b32_e32 v33, v0
	v_mov_b32_e32 v34, v0
	v_mov_b32_e32 v35, v0
	v_mov_b32_e32 v36, v0
	v_mov_b32_e32 v37, v0
	v_mov_b32_e32 v38, v0
	v_mov_b32_e32 v39, v0
	v_mov_b32_e32 v40, v0
	v_mov_b32_e32 v41, v0
	v_mov_b32_e32 v42, v0
	v_mov_b32_e32 v43, v0
	v_mov_b32_e32 v44, v0
	v_mov_b32_e32 v45, v0
	v_mov_b32_e32 v46, v0
	v_mov_b32_e32 v47, v0
	v_mov_b32_e32 v48, v0
	v_mov_b32_e32 v49, v0
	v_mov_b32_e32 v50, v0
	v_mov_b32_e32 v51, v0
	v_mov_b32_e32 v52, v0
	v_mov_b32_e32 v53, v0
	v_mov_b32_e32 v54, v0
	v_mov_b32_e32 v55, v0
	v_mov_b32_e32 v56, v0
	v_mov_b32_e32 v57, v0
	v_mov_b32_e32 v58, v0
	v_mov_b32_e32 v59, v0
	v_mov_b32_e32 v60, v0
	v_mov_b32_e32 v61, v0
	v_mov_b32_e32 v62, v0
	v_mov_b32_e32 v63, v0
	v_mov_b32_e32 v64, v0
	v_mov_b32_e32 v65, v0
	v_mov_b32_e32 v66, v0
	v_mov_b32_e32 v67, v0
	v_mov_b32_e32 v68, v0
	v_mov_b32_e32 v69, v0
	v_mov_b32_e32 v70, v0
	v_mov_b32_e32 v71, v0
	v_mov_b32_e32 v72, v0
	v_mov_b32_e32 v73, v0
	v_mov_b32_e32 v74, v0
	v_mov_b32_e32 v75, v0
	v_mov_b32_e32 v76, v0
	v_mov_b32_e32 v77, v0
	v_mov_b32_e32 v78, v0
	v_mov_b32_e32 v79, v0
	v_mov_b32_e32 v80, v0
	v_mov_b32_e32 v81, v0
	v_mov_b32_e32 v82, v0
	v_mov_b32_e32 v83, v0
	v_mov_b32_e32 v84, v0
	v_mov_b32_e32 v85, v0
	v_mov_b32_e32 v86, v0
	v_mov_b32_e32 v87, v0
	v_mov_b32_e32 v88, v0
	v_mov_b32_e32 v89, v0
	v_mov_b32_e32 v90, v0
	v_mov_b32_e32 v91, v0
	v_mov_b32_e32 v92, v0
	v_mov_b32_e32 v93, v0
	v_mov_b32_e32 v94, v0
	v_mov_b32_e32 v95, v0
	v_mov_b32_e32 v96, v0
	v_mov_b32_e32 v97, v0
	v_mov_b32_e32 v98, v0
	v_mov_b32_e32 v99, v0
	v_mov_b32_e32 v100, v0
	v_mov_b32_e32 v101, v0
	v_mov_b32_e32 v102, v0
	v_mov_b32_e32 v103, v0
	v_mov_b32_e32 v104, v0
	v_mov_b32_e32 v105, v0
	v_mov_b32_e32 v106, v0
	v_mov_b32_e32 v107, v0
	v_mov_b32_e32 v108, v0
	v_mov_b32_e32 v109, v0
	v_mov_b32_e32 v110, v0
	v_mov_b32_e32 v111, v0
	v_mov_b32_e32 v114, v0
	v_mov_b32_e32 v115, v0
	v_mov_b32_e32 v116, v0
	v_mov_b32_e32 v117, v0
	v_mov_b32_e32 v118, v0
	v_mov_b32_e32 v119, v0
	v_mov_b32_e32 v120, v0
	v_mov_b32_e32 v121, v0
	v_mov_b32_e32 v122, v0
	v_mov_b32_e32 v123, v0
	v_mov_b32_e32 v124, v0
	v_mov_b32_e32 v125, v0
	v_mov_b32_e32 v126, v0
	v_mov_b32_e32 v127, v0
	v_mov_b32_e32 v128, v0
	v_mov_b32_e32 v129, v0
	s_add_i32 s9, s8, 0xfffe8000
	s_and_b32 s10, s8, 0x18000
	s_waitcnt vmcnt(8)
	s_barrier
	s_and_b32 s9, s9, 0x18000
	s_add_i32 s10, s7, s10
	v_add_u32_e32 v112, s9, v135
	v_or_b32_e32 v139, s9, v137
	s_add_i32 s18, s10, 0x400
	s_add_i32 s11, s10, 0x800
	s_add_i32 s9, s10, 0xc00
	s_add_i32 s8, s8, 0x8000
	s_cmp_eq_u32 s8, 0x100000
	ds_read_b128 v[186:189], v112
	ds_read_b128 v[158:161], v139
	ds_read_b128 v[162:165], v139 offset:1024
	ds_read_b128 v[166:169], v139 offset:2048
	ds_read_b128 v[182:185], v139 offset:3072
	ds_read_b128 v[190:193], v112 offset:1024
	ds_read_b128 v[194:197], v112 offset:2048
	ds_read_b128 v[198:201], v112 offset:3072
	ds_read_b128 v[232:235], v112 offset:4096
	ds_read_b128 v[236:239], v112 offset:5120
	ds_read_b128 v[240:243], v112 offset:6144
	ds_read_b128 v[244:247], v112 offset:7168
	s_mov_b32 m0, s10
	s_nop 0
	global_load_lds_dwordx4 v[154:155], off
	v_lshl_add_u64 v[154:155], v[154:155], 0, 64
	s_mov_b32 m0, s18
	s_nop 0
	global_load_lds_dwordx4 v[152:153], off
	v_lshl_add_u64 v[152:153], v[152:153], 0, 64
	s_mov_b32 m0, s11
	s_nop 0
	global_load_lds_dwordx4 v[150:151], off
	v_lshl_add_u64 v[150:151], v[150:151], 0, 64
	s_mov_b32 m0, s9
	s_nop 0
	global_load_lds_dwordx4 v[148:149], off
	v_lshl_add_u64 v[148:149], v[148:149], 0, 64
	s_waitcnt lgkmcnt(4)
	v_mfma_f32_16x16x32_bf16 v[126:129], v[158:161], v[186:189], v[126:129]
	v_mfma_f32_16x16x32_bf16 v[122:125], v[162:165], v[186:189], v[122:125]
	v_mfma_f32_16x16x32_bf16 v[118:121], v[166:169], v[186:189], v[118:121]
	v_mfma_f32_16x16x32_bf16 v[114:117], v[182:185], v[186:189], v[114:117]
	v_mfma_f32_16x16x32_bf16 v[108:111], v[158:161], v[190:193], v[108:111]
	v_mfma_f32_16x16x32_bf16 v[104:107], v[162:165], v[190:193], v[104:107]
	v_mfma_f32_16x16x32_bf16 v[100:103], v[166:169], v[190:193], v[100:103]
	v_mfma_f32_16x16x32_bf16 v[96:99], v[182:185], v[190:193], v[96:99]
	v_mfma_f32_16x16x32_bf16 v[92:95], v[158:161], v[194:197], v[92:95]
	v_mfma_f32_16x16x32_bf16 v[88:91], v[162:165], v[194:197], v[88:91]
	v_mfma_f32_16x16x32_bf16 v[84:87], v[166:169], v[194:197], v[84:87]
	v_mfma_f32_16x16x32_bf16 v[80:83], v[182:185], v[194:197], v[80:83]
	v_mfma_f32_16x16x32_bf16 v[76:79], v[158:161], v[198:201], v[76:79]
	v_mfma_f32_16x16x32_bf16 v[72:75], v[162:165], v[198:201], v[72:75]
	v_mfma_f32_16x16x32_bf16 v[68:71], v[166:169], v[198:201], v[68:71]
	v_mfma_f32_16x16x32_bf16 v[64:67], v[182:185], v[198:201], v[64:67]

.LBB0_306:
	v_mov_b32_e32 v118, v157
	s_add_i32 s6, s10, -6
	v_readfirstlane_b32 s4, v118
	s_ashr_i32 s5, s4, 1
	s_lshl_b32 s9, s11, 8
	s_and_b32 s5, s5, 0xffffff80
	v_bfe_u32 v123, v118, 4, 2
	s_add_i32 s8, s5, s9
	s_lshl_b32 s84, s6, 8
	s_and_b32 s5, s4, 0xc0
	s_lshl_b32 s4, s4, 8
	v_and_b32_e32 v119, 63, v118
	s_or_b32 s79, s5, s84
	s_and_b32 s78, s4, 0xffffc000
	v_lshlrev_b32_e32 v0, 3, v123
	v_and_b32_e32 v171, 15, v118
	s_mov_b64 s[4:5], -1
	s_cmp_gt_u32 s6, 3
	v_lshrrev_b32_e32 v170, 5, v119
	v_and_b32_e32 v173, 8, v0
	s_cbranch_scc0 .LBB0_308
	v_mov_b32_e32 v2, v157
	s_add_i32 s86, s84, 0xffffff00
	v_readfirstlane_b32 s31, v2
	s_ashr_i32 s85, s31, 6
	s_lshl_b32 s74, s85, 2
	s_cmp_lt_i32 s85, 4
	s_cselect_b64 s[4:5], -1, 0
	s_and_b32 s70, s31, 0xffffffc0
	s_and_b64 s[6:7], s[4:5], exec
	s_cselect_b32 s6, s9, s86
	s_add_i32 s6, s6, s70
	s_and_b64 s[4:5], s[4:5], exec
	s_cselect_b32 s70, s59, s19
	s_cselect_b32 s71, s58, s18
	s_ashr_i32 s7, s6, 31
	s_lshl_b64 s[4:5], s[6:7], 8
	s_add_u32 s4, s71, s4
	s_addc_u32 s5, s70, s5
	s_or_b32 s70, s74, 1
	s_cmp_lt_i32 s70, 16
	s_cselect_b64 s[6:7], -1, 0
	s_lshl_b32 s72, s70, 4
	s_and_b64 s[70:71], s[6:7], exec
	s_cselect_b32 s70, s9, s86
	s_add_i32 s70, s70, s72
	s_and_b64 s[6:7], s[6:7], exec
	s_cselect_b32 s72, s59, s19
	s_cselect_b32 s73, s58, s18
	s_ashr_i32 s71, s70, 31
	s_lshl_b64 s[6:7], s[70:71], 8
	s_add_u32 s6, s73, s6
	s_addc_u32 s7, s72, s7
	s_or_b32 s72, s74, 2
	s_cmp_lt_i32 s72, 16
	s_cselect_b64 s[70:71], -1, 0
	s_lshl_b32 s75, s72, 4
	s_and_b64 s[72:73], s[70:71], exec
	s_cselect_b32 s72, s9, s86
	s_add_i32 s72, s72, s75
	s_and_b64 s[70:71], s[70:71], exec
	s_cselect_b32 s75, s59, s19
	s_cselect_b32 s87, s58, s18
	s_ashr_i32 s73, s72, 31
	s_lshl_b64 s[70:71], s[72:73], 8
	s_add_u32 s70, s87, s70
	s_addc_u32 s71, s75, s71
	s_or_b32 s74, s74, 3
	s_cmp_lt_i32 s74, 16
	s_cselect_b64 s[72:73], -1, 0
	s_lshl_b32 s87, s74, 4
	s_and_b64 s[74:75], s[72:73], exec
	s_cselect_b32 s74, s9, s86
	s_add_i32 s74, s74, s87
	s_and_b64 s[72:73], s[72:73], exec
	v_lshrrev_b32_e32 v3, 4, v2
	s_cselect_b32 s86, s59, s19
	s_cselect_b32 s87, s58, s18
	s_ashr_i32 s75, s74, 31
	v_sub_u32_e32 v1, 0, v3
	s_lshl_b64 s[72:73], s[74:75], 8
	v_lshlrev_b32_e32 v0, 6, v2
	v_xor_b32_e32 v1, v2, v1
	s_add_u32 s72, s87, s72
	v_and_b32_e32 v0, 0xf00, v0
	v_lshlrev_b32_e32 v1, 4, v1
	s_addc_u32 s73, s86, s73
	s_lshl_b32 s74, s85, 12
	v_and_or_b32 v112, v1, 48, v0
	s_mov_b32 m0, s74
	s_waitcnt vmcnt(0)
	v_lshl_add_u64 v[32:33], s[4:5], 0, v[112:113]
	global_load_lds_dwordx4 v112, s[4:5]
	s_or_b32 m0, s74, 0x400
	v_lshl_add_u64 v[34:35], s[6:7], 0, v[112:113]
	global_load_lds_dwordx4 v112, s[6:7]
	s_or_b32 m0, s74, 0x800
	v_lshl_add_u64 v[0:1], v[32:33], 0, 64
	global_load_lds_dwordx4 v112, s[70:71]
	s_or_b32 m0, s74, 0xc00
	v_lshl_add_u64 v[36:37], s[70:71], 0, v[112:113]
	global_load_lds_dwordx4 v112, s[72:73]
	s_add_i32 m0, s74, 0x8000
	v_lshl_add_u64 v[38:39], s[72:73], 0, v[112:113]
	global_load_lds_dwordx4 v[0:1], off
	v_lshl_add_u64 v[0:1], v[34:35], 0, 64
	s_add_i32 m0, s74, 0x8400
	s_lshr_b32 s4, s31, 1
	global_load_lds_dwordx4 v[0:1], off
	v_lshl_add_u64 v[0:1], v[36:37], 0, 64
	s_add_i32 m0, s74, 0x8800
	v_and_b32_e32 v4, 15, v2
	global_load_lds_dwordx4 v[0:1], off
	v_lshl_add_u64 v[0:1], v[38:39], 0, 64
	s_add_i32 m0, s74, 0x8c00
	s_and_b32 s4, s4, 0x3ffff80
	global_load_lds_dwordx4 v[0:1], off
	s_add_i32 m0, s74, 0x10000
	v_lshl_add_u64 v[0:1], v[32:33], 0, s[90:91]
	global_load_lds_dwordx4 v[0:1], off
	v_lshl_add_u64 v[0:1], v[34:35], 0, s[90:91]
	s_add_i32 m0, s74, 0x10400
	s_add_i32 s5, s74, 0x18800
	global_load_lds_dwordx4 v[0:1], off
	v_lshl_add_u64 v[0:1], v[36:37], 0, s[90:91]
	s_add_i32 m0, s74, 0x10800
	v_lshl_add_u64 v[32:33], v[32:33], 0, s[76:77]
	global_load_lds_dwordx4 v[0:1], off
	v_lshl_add_u64 v[0:1], v[38:39], 0, s[90:91]
	s_add_i32 m0, s74, 0x10c00
	v_lshl_add_u64 v[34:35], v[34:35], 0, s[76:77]
	global_load_lds_dwordx4 v[0:1], off
	v_lshrrev_b32_e32 v0, 2, v2
	v_sub_u32_e32 v0, 0, v0
	v_bitop3_b32 v0, v3, 3, v0 bitop3:0x48
	v_or_b32_e32 v1, s4, v4
	v_lshlrev_b32_e32 v0, 4, v0
	s_and_b32 s4, s31, 0xc0
	v_lshl_or_b32 v112, v1, 6, v0
	v_or_b32_e32 v1, s4, v4
	v_lshl_or_b32 v120, v1, 6, v0
	s_waitcnt vmcnt(8)
	s_barrier
	v_or_b32_e32 v40, 0x4000, v120
	ds_read_b128 v[0:3], v40
	ds_read_b128 v[4:7], v40 offset:1024
	ds_read_b128 v[8:11], v40 offset:2048
	ds_read_b128 v[12:15], v40 offset:3072
	ds_read_b128 v[16:19], v112
	ds_read_b128 v[20:23], v112 offset:1024
	ds_read_b128 v[24:27], v112 offset:2048
	ds_read_b128 v[28:31], v112 offset:3072
	s_add_i32 m0, s74, 0x18000
	s_add_i32 s4, s74, 0x18c00
	s_add_i32 s74, s74, 0x18400
	global_load_lds_dwordx4 v[32:33], off
	s_mov_b32 m0, s74
	v_lshl_add_u64 v[36:37], v[36:37], 0, s[76:77]
	global_load_lds_dwordx4 v[34:35], off
	s_mov_b32 m0, s5
	v_lshl_add_u64 v[38:39], v[38:39], 0, s[76:77]
	global_load_lds_dwordx4 v[36:37], off
	s_mov_b32 m0, s4
	v_add_u32_e32 v121, 0x8000, v112
	global_load_lds_dwordx4 v[38:39], off
	s_waitcnt lgkmcnt(0)
	ds_read_b128 v[80:83], v112 offset:4096
	ds_read_b128 v[84:87], v112 offset:5120
	ds_read_b128 v[88:91], v112 offset:6144
	ds_read_b128 v[92:95], v112 offset:7168
	s_waitcnt lgkmcnt(0)
	s_waitcnt vmcnt(8)
	s_barrier
	v_mfma_f32_16x16x32_bf16 v[32:35], v[16:19], v[0:3], 0
	v_or_b32_e32 v122, 0xc000, v120
	s_mov_b32 s6, 0x358637bd
	v_mfma_f32_16x16x32_bf16 v[36:39], v[16:19], v[4:7], 0
	s_add_i32 s4, s79, 0xfffffc00
	s_ashr_i32 s4, s4, 6
	s_and_b32 s5, s11, -16
	v_mfma_f32_16x16x32_bf16 v[40:43], v[16:19], v[8:11], 0
	s_add_i32 s4, s4, s5
	s_ashr_i32 s5, s4, 31
	s_lshl_b64 s[4:5], s[4:5], 19
	v_mfma_f32_16x16x32_bf16 v[16:19], v[16:19], v[12:15], 0
	s_add_u32 s4, s66, s4
	s_addc_u32 s5, s67, s5
	v_mfma_f32_16x16x32_bf16 v[44:47], v[20:23], v[0:3], 0
	v_mfma_f32_16x16x32_bf16 v[48:51], v[20:23], v[4:7], 0
	v_mfma_f32_16x16x32_bf16 v[52:55], v[20:23], v[8:11], 0
	v_mfma_f32_16x16x32_bf16 v[20:23], v[20:23], v[12:15], 0
	v_mfma_f32_16x16x32_bf16 v[56:59], v[24:27], v[0:3], 0
	v_mfma_f32_16x16x32_bf16 v[60:63], v[24:27], v[4:7], 0
	v_mfma_f32_16x16x32_bf16 v[64:67], v[24:27], v[8:11], 0
	v_mfma_f32_16x16x32_bf16 v[24:27], v[24:27], v[12:15], 0
	v_mfma_f32_16x16x32_bf16 v[68:71], v[28:31], v[0:3], 0
	v_mfma_f32_16x16x32_bf16 v[72:75], v[28:31], v[4:7], 0
	v_mfma_f32_16x16x32_bf16 v[76:79], v[28:31], v[8:11], 0
	v_mfma_f32_16x16x32_bf16 v[28:31], v[28:31], v[12:15], 0
	v_mfma_f32_16x16x32_bf16 v[114:117], v[84:87], v[4:7], 0
	v_mfma_f32_16x16x32_bf16 v[96:99], v[80:83], v[0:3], 0
	v_mfma_f32_16x16x32_bf16 v[100:103], v[80:83], v[4:7], 0
	v_mfma_f32_16x16x32_bf16 v[104:107], v[80:83], v[8:11], 0
	v_mfma_f32_16x16x32_bf16 v[80:83], v[80:83], v[12:15], 0
	v_mfma_f32_16x16x32_bf16 v[108:111], v[84:87], v[0:3], 0
	v_mfma_f32_16x16x32_bf16 v[124:127], v[84:87], v[8:11], 0
	v_mfma_f32_16x16x32_bf16 v[84:87], v[84:87], v[12:15], 0
	v_mfma_f32_16x16x32_bf16 v[128:131], v[88:91], v[0:3], 0
	v_mfma_f32_16x16x32_bf16 v[132:135], v[88:91], v[4:7], 0
	v_mfma_f32_16x16x32_bf16 v[136:139], v[88:91], v[8:11], 0
	v_mfma_f32_16x16x32_bf16 v[88:91], v[88:91], v[12:15], 0
	v_mfma_f32_16x16x32_bf16 v[0:3], v[92:95], v[0:3], 0
	v_mfma_f32_16x16x32_bf16 v[4:7], v[92:95], v[4:7], 0
	v_mfma_f32_16x16x32_bf16 v[8:11], v[92:95], v[8:11], 0
	v_mfma_f32_16x16x32_bf16 v[12:15], v[92:95], v[12:15], 0
	ds_read_b128 v[92:95], v122
	ds_read_b128 v[140:143], v122 offset:1024
	ds_read_b128 v[144:147], v122 offset:2048
	ds_read_b128 v[148:151], v122 offset:3072
	ds_read_b128 v[152:155], v121
	ds_read_b128 v[158:161], v121 offset:1024
	ds_read_b128 v[162:165], v121 offset:2048
	ds_read_b128 v[166:169], v121 offset:3072
	v_or_b32_e32 v122, 0x14000, v120
	s_waitcnt lgkmcnt(0)
	s_nop 0
	v_mfma_f32_16x16x32_bf16 v[32:35], v[152:155], v[92:95], v[32:35]
	v_mfma_f32_16x16x32_bf16 v[36:39], v[152:155], v[140:143], v[36:39]
	v_mfma_f32_16x16x32_bf16 v[40:43], v[152:155], v[144:147], v[40:43]
	v_mfma_f32_16x16x32_bf16 v[16:19], v[152:155], v[148:151], v[16:19]
	v_mfma_f32_16x16x32_bf16 v[44:47], v[158:161], v[92:95], v[44:47]
	v_mfma_f32_16x16x32_bf16 v[48:51], v[158:161], v[140:143], v[48:51]
	v_mfma_f32_16x16x32_bf16 v[52:55], v[158:161], v[144:147], v[52:55]
	v_mfma_f32_16x16x32_bf16 v[20:23], v[158:161], v[148:151], v[20:23]
	v_mfma_f32_16x16x32_bf16 v[56:59], v[162:165], v[92:95], v[56:59]
	v_mfma_f32_16x16x32_bf16 v[60:63], v[162:165], v[140:143], v[60:63]
	v_mfma_f32_16x16x32_bf16 v[64:67], v[162:165], v[144:147], v[64:67]
	v_mfma_f32_16x16x32_bf16 v[24:27], v[162:165], v[148:151], v[24:27]
	v_mfma_f32_16x16x32_bf16 v[68:71], v[166:169], v[92:95], v[68:71]
	v_mfma_f32_16x16x32_bf16 v[72:75], v[166:169], v[140:143], v[72:75]
	v_mfma_f32_16x16x32_bf16 v[76:79], v[166:169], v[144:147], v[76:79]
	v_mfma_f32_16x16x32_bf16 v[28:31], v[166:169], v[148:151], v[28:31]
	ds_read_b128 v[152:155], v121 offset:4096
	ds_read_b128 v[158:161], v121 offset:5120
	ds_read_b128 v[162:165], v121 offset:6144
	ds_read_b128 v[166:169], v121 offset:7168
	s_waitcnt lgkmcnt(0)
	s_waitcnt vmcnt(4)
	s_barrier
	v_mfma_f32_16x16x32_bf16 v[114:117], v[158:161], v[140:143], v[114:117]
	v_add_u32_e32 v121, 0x10000, v112
	v_add_u32_e32 v112, 0x18000, v112
	v_mfma_f32_16x16x32_bf16 v[96:99], v[152:155], v[92:95], v[96:99]
	v_mfma_f32_16x16x32_bf16 v[100:103], v[152:155], v[140:143], v[100:103]
	v_mfma_f32_16x16x32_bf16 v[104:107], v[152:155], v[144:147], v[104:107]
	v_mfma_f32_16x16x32_bf16 v[80:83], v[152:155], v[148:151], v[80:83]
	v_mfma_f32_16x16x32_bf16 v[108:111], v[158:161], v[92:95], v[108:111]
	v_mfma_f32_16x16x32_bf16 v[124:127], v[158:161], v[144:147], v[124:127]
	v_mfma_f32_16x16x32_bf16 v[84:87], v[158:161], v[148:151], v[84:87]
	v_mfma_f32_16x16x32_bf16 v[128:131], v[162:165], v[92:95], v[128:131]
	v_mfma_f32_16x16x32_bf16 v[132:135], v[162:165], v[140:143], v[132:135]
	v_mfma_f32_16x16x32_bf16 v[136:139], v[162:165], v[144:147], v[136:139]
	v_mfma_f32_16x16x32_bf16 v[88:91], v[162:165], v[148:151], v[88:91]
	v_mfma_f32_16x16x32_bf16 v[0:3], v[166:169], v[92:95], v[0:3]
	v_mfma_f32_16x16x32_bf16 v[4:7], v[166:169], v[140:143], v[4:7]
	v_mfma_f32_16x16x32_bf16 v[8:11], v[166:169], v[144:147], v[8:11]
	v_mfma_f32_16x16x32_bf16 v[12:15], v[166:169], v[148:151], v[12:15]
	ds_read_b128 v[92:95], v122
	ds_read_b128 v[140:143], v122 offset:1024
	ds_read_b128 v[144:147], v122 offset:2048
	ds_read_b128 v[148:151], v122 offset:3072
	ds_read_b128 v[152:155], v121
	ds_read_b128 v[158:161], v121 offset:1024
	ds_read_b128 v[162:165], v121 offset:2048
	ds_read_b128 v[166:169], v121 offset:3072
	s_nop 0
	s_waitcnt lgkmcnt(0)
	s_nop 0
	v_mfma_f32_16x16x32_bf16 v[32:35], v[152:155], v[92:95], v[32:35]
	v_mfma_f32_16x16x32_bf16 v[36:39], v[152:155], v[140:143], v[36:39]
	v_mfma_f32_16x16x32_bf16 v[40:43], v[152:155], v[144:147], v[40:43]
	v_mfma_f32_16x16x32_bf16 v[16:19], v[152:155], v[148:151], v[16:19]
	v_mfma_f32_16x16x32_bf16 v[44:47], v[158:161], v[92:95], v[44:47]
	v_mfma_f32_16x16x32_bf16 v[48:51], v[158:161], v[140:143], v[48:51]
	v_mfma_f32_16x16x32_bf16 v[52:55], v[158:161], v[144:147], v[52:55]
	v_mfma_f32_16x16x32_bf16 v[20:23], v[158:161], v[148:151], v[20:23]
	v_mfma_f32_16x16x32_bf16 v[56:59], v[162:165], v[92:95], v[56:59]
	v_mfma_f32_16x16x32_bf16 v[60:63], v[162:165], v[140:143], v[60:63]
	v_mfma_f32_16x16x32_bf16 v[64:67], v[162:165], v[144:147], v[64:67]
	v_mfma_f32_16x16x32_bf16 v[24:27], v[162:165], v[148:151], v[24:27]
	v_mfma_f32_16x16x32_bf16 v[68:71], v[166:169], v[92:95], v[68:71]
	v_mfma_f32_16x16x32_bf16 v[72:75], v[166:169], v[140:143], v[72:75]
	v_mfma_f32_16x16x32_bf16 v[152:155], v[166:169], v[144:147], v[76:79]
	v_mfma_f32_16x16x32_bf16 v[28:31], v[166:169], v[148:151], v[28:31]
	ds_read_b128 v[76:79], v121 offset:4096
	ds_read_b128 v[158:161], v121 offset:5120
	ds_read_b128 v[162:165], v121 offset:6144
	ds_read_b128 v[166:169], v121 offset:7168
	s_waitcnt lgkmcnt(0)
	s_waitcnt vmcnt(0)
	s_barrier
	v_mfma_f32_16x16x32_bf16 v[114:117], v[158:161], v[140:143], v[114:117]
	v_mfma_f32_16x16x32_bf16 v[174:177], v[76:79], v[92:95], v[96:99]
	v_mfma_f32_16x16x32_bf16 v[182:185], v[76:79], v[140:143], v[100:103]
	v_mfma_f32_16x16x32_bf16 v[186:189], v[76:79], v[144:147], v[104:107]
	v_mfma_f32_16x16x32_bf16 v[190:193], v[76:79], v[148:151], v[80:83]
	v_mfma_f32_16x16x32_bf16 v[194:197], v[158:161], v[92:95], v[108:111]
	v_mfma_f32_16x16x32_bf16 v[124:127], v[158:161], v[144:147], v[124:127]
	v_mfma_f32_16x16x32_bf16 v[158:161], v[158:161], v[148:151], v[84:87]
	v_mfma_f32_16x16x32_bf16 v[128:131], v[162:165], v[92:95], v[128:131]
	s_nop 1
	v_or_b32_e32 v84, 0x1c000, v120
	v_mfma_f32_16x16x32_bf16 v[132:135], v[162:165], v[140:143], v[132:135]
	v_mfma_f32_16x16x32_bf16 v[136:139], v[162:165], v[144:147], v[136:139]
	v_mfma_f32_16x16x32_bf16 v[162:165], v[162:165], v[148:151], v[88:91]
	v_mfma_f32_16x16x32_bf16 v[0:3], v[166:169], v[92:95], v[0:3]
	v_mfma_f32_16x16x32_bf16 v[4:7], v[166:169], v[140:143], v[4:7]
	v_mfma_f32_16x16x32_bf16 v[140:143], v[166:169], v[144:147], v[8:11]
	v_mfma_f32_16x16x32_bf16 v[144:147], v[166:169], v[148:151], v[12:15]
	ds_read_b128 v[8:11], v84
	ds_read_b128 v[148:151], v84 offset:1024
	ds_read_b128 v[166:169], v84 offset:2048
	ds_read_b128 v[198:201], v84 offset:3072
	ds_read_b128 v[12:15], v112
	ds_read_b128 v[76:79], v112 offset:1024
	ds_read_b128 v[80:83], v112 offset:2048
	ds_read_b128 v[202:205], v112 offset:3072
	s_nop 0
	s_waitcnt lgkmcnt(0)
	s_nop 0
	v_mfma_f32_16x16x32_bf16 v[206:209], v[12:15], v[8:11], v[32:35]
	v_mfma_f32_16x16x32_bf16 v[210:213], v[12:15], v[148:151], v[36:39]
	v_mfma_f32_16x16x32_bf16 v[214:217], v[12:15], v[166:169], v[40:43]
	v_mfma_f32_16x16x32_bf16 v[218:221], v[12:15], v[198:201], v[16:19]
	v_mfma_f32_16x16x32_bf16 v[108:111], v[76:79], v[8:11], v[44:47]
	v_mfma_f32_16x16x32_bf16 v[104:107], v[76:79], v[148:151], v[48:51]
	v_mfma_f32_16x16x32_bf16 v[100:103], v[76:79], v[166:169], v[52:55]
	v_mfma_f32_16x16x32_bf16 v[96:99], v[76:79], v[198:201], v[20:23]
	v_mfma_f32_16x16x32_bf16 v[84:87], v[80:83], v[166:169], v[64:67]
	v_mfma_f32_16x16x32_bf16 v[76:79], v[202:205], v[8:11], v[68:71]
	v_mfma_f32_16x16x32_bf16 v[72:75], v[202:205], v[148:151], v[72:75]
	v_mfma_f32_16x16x32_bf16 v[68:71], v[202:205], v[166:169], v[152:155]
	v_mfma_f32_16x16x32_bf16 v[64:67], v[202:205], v[198:201], v[28:31]
	ds_read_b128 v[12:15], v112 offset:4096
	ds_read_b128 v[16:19], v112 offset:5120
	ds_read_b128 v[152:155], v112 offset:6144
	ds_read_b128 v[202:205], v112 offset:7168
	s_waitcnt lgkmcnt(0)
	s_barrier
	v_mfma_f32_16x16x32_bf16 v[40:43], v[16:19], v[148:151], v[114:117]
	v_lshlrev_b32_e32 v112, 8, v171
	v_add3_u32 v112, s78, v112, v173
	s_nop 0
	v_lshl_or_b32 v116, v123, 2, s8
	v_ashrrev_i32_e32 v117, 31, v116
	v_lshl_add_u64 v[114:115], v[116:117], 3, s[42:43]
	v_mfma_f32_16x16x32_bf16 v[36:39], v[16:19], v[166:169], v[124:127]
	v_mfma_f32_16x16x32_bf16 v[28:31], v[152:155], v[8:11], v[128:131]
	s_nop 1
	global_load_dwordx4 v[124:127], v[114:115], off offset:16
	global_load_dwordx4 v[128:131], v[114:115], off
	s_waitcnt vmcnt(0)
	v_mov_b32_e32 v114, v129
	v_mov_b32_e32 v115, v130
	v_mov_b32_e32 v129, v131
	v_pk_add_f32 v[120:121], v[114:115], v[128:129]
	v_mov_b64_e32 v[114:115], s[6:7]
	v_pk_fma_f32 v[120:121], v[120:121], s[80:81], v[114:115] op_sel_hi:[1,0,0]
	v_mfma_f32_16x16x32_bf16 v[92:95], v[80:83], v[8:11], v[56:59]
	v_mul_f32_e32 v117, 0x4b800000, v120
	v_cmp_gt_f32_e64 s[6:7], s28, v120
	v_cmp_gt_f32_e32 vcc, s28, v121
	v_mfma_f32_16x16x32_bf16 v[88:91], v[80:83], v[148:151], v[60:63]
	v_cndmask_b32_e64 v117, v120, v117, s[6:7]
	v_rsq_f32_e32 v120, v117
	v_mul_f32_e32 v117, 0x4b800000, v121
	v_cndmask_b32_e32 v117, v121, v117, vcc
	v_rsq_f32_e32 v121, v117
	v_mfma_f32_16x16x32_bf16 v[80:83], v[80:83], v[198:201], v[24:27]
	v_mul_f32_e64 v128, v120, s82
	v_mul_f32_e64 v129, v121, s82
	v_cndmask_b32_e32 v121, v121, v129, vcc
	v_cndmask_b32_e64 v120, v120, v128, s[6:7]
	v_mov_b32_e32 v128, v125
	v_mov_b32_e32 v129, v126
	v_mov_b32_e32 v125, v127
	v_pk_add_f32 v[124:125], v[128:129], v[124:125]
	v_pk_mul_f32 v[128:129], v[206:207], v[120:121]
	v_pk_fma_f32 v[124:125], v[124:125], s[80:81], v[114:115] op_sel_hi:[1,0,0]
	v_cvt_pk_bf16_f32 v128, v128, v129
	v_mul_f32_e32 v117, 0x4b800000, v124
	v_cmp_gt_f32_e64 s[6:7], s28, v124
	v_cmp_gt_f32_e32 vcc, s28, v125
	v_pk_mul_f32 v[130:131], v[210:211], v[120:121]
	v_cndmask_b32_e64 v117, v124, v117, s[6:7]
	v_rsq_f32_e32 v124, v117
	v_mul_f32_e32 v117, 0x4b800000, v125
	v_cndmask_b32_e32 v117, v125, v117, vcc
	v_rsq_f32_e32 v125, v117
	v_xor_b32_e32 v117, v170, v171
	v_lshl_add_u32 v117, v117, 4, v112
	v_cvt_pk_bf16_f32 v130, v130, v131
	v_pk_mul_f32 v[126:127], v[124:125], s[82:83] op_sel_hi:[1,0]
	v_mfma_f32_16x16x32_bf16 v[52:55], v[12:15], v[166:169], v[186:189]
	v_cndmask_b32_e32 v125, v125, v127, vcc
	v_cndmask_b32_e64 v124, v124, v126, s[6:7]
	v_pk_mul_f32 v[126:127], v[208:209], v[124:125]
	v_mfma_f32_16x16x32_bf16 v[48:51], v[12:15], v[198:201], v[190:193]
	v_cvt_pk_bf16_f32 v129, v126, v127
	v_pk_mul_f32 v[126:127], v[212:213], v[124:125]
	s_nop 0
	v_cvt_pk_bf16_f32 v131, v126, v127
	ds_write2st64_b64 v117, v[128:129], v[130:131] offset1:8
	v_pk_mul_f32 v[126:127], v[216:217], v[124:125]
	v_pk_mul_f32 v[128:129], v[214:215], v[120:121]
	v_pk_mul_f32 v[124:125], v[220:221], v[124:125]
	v_pk_mul_f32 v[120:121], v[218:219], v[120:121]
	v_cvt_pk_bf16_f32 v128, v128, v129
	v_cvt_pk_bf16_f32 v129, v126, v127
	v_cvt_pk_bf16_f32 v120, v120, v121
	v_cvt_pk_bf16_f32 v121, v124, v125
	ds_write2st64_b64 v117, v[128:129], v[120:121] offset0:16 offset1:24
	v_or_b32_e32 v120, 16, v116
	v_ashrrev_i32_e32 v121, 31, v120
	v_lshl_add_u64 v[120:121], v[120:121], 3, s[42:43]
	global_load_dwordx4 v[124:127], v[120:121], off offset:16
	global_load_dwordx4 v[128:131], v[120:121], off
	v_mfma_f32_16x16x32_bf16 v[60:63], v[12:15], v[8:11], v[174:177]
	s_waitcnt vmcnt(0)
	v_mov_b32_e32 v120, v129
	v_mov_b32_e32 v121, v130
	v_mov_b32_e32 v129, v131
	v_pk_add_f32 v[120:121], v[120:121], v[128:129]
	v_mfma_f32_16x16x32_bf16 v[56:59], v[12:15], v[148:151], v[182:185]
	v_fma_f32 v120, v120, s80, v114
	v_fma_f32 v121, v121, s80, v114
	v_mul_f32_e32 v117, 0x4b800000, v120
	v_cmp_gt_f32_e64 s[6:7], s28, v120
	v_cmp_gt_f32_e32 vcc, s28, v121
	v_mfma_f32_16x16x32_bf16 v[32:35], v[16:19], v[198:201], v[158:161]
	v_cndmask_b32_e64 v117, v120, v117, s[6:7]
	v_rsq_f32_e32 v120, v117
	v_mul_f32_e32 v117, 0x4b800000, v121
	v_cndmask_b32_e32 v117, v121, v117, vcc
	v_rsq_f32_e32 v121, v117
	v_mfma_f32_16x16x32_bf16 v[44:47], v[16:19], v[8:11], v[194:197]
	v_mul_f32_e64 v128, v120, s82
	v_mul_f32_e64 v129, v121, s82
	v_cndmask_b32_e32 v121, v121, v129, vcc
	v_cndmask_b32_e64 v120, v120, v128, s[6:7]
	v_mov_b32_e32 v128, v125
	v_mov_b32_e32 v129, v126
	v_mov_b32_e32 v125, v127
	v_pk_add_f32 v[124:125], v[128:129], v[124:125]
	v_pk_mul_f32 v[100:101], v[100:101], v[120:121]
	v_pk_fma_f32 v[124:125], v[124:125], s[80:81], v[114:115] op_sel_hi:[1,0,0]
	v_pk_mul_f32 v[96:97], v[96:97], v[120:121]
	v_mul_f32_e32 v117, 0x4b800000, v124
	v_cmp_gt_f32_e64 s[6:7], s28, v124
	v_cmp_gt_f32_e32 vcc, s28, v125
	v_cvt_pk_bf16_f32 v100, v100, v101
	v_cndmask_b32_e64 v117, v124, v117, s[6:7]
	v_rsq_f32_e32 v124, v117
	v_mul_f32_e32 v117, 0x4b800000, v125
	v_cndmask_b32_e32 v117, v125, v117, vcc
	v_rsq_f32_e32 v125, v117
	v_bitop3_b32 v117, v170, v171, 2 bitop3:0x36
	v_lshl_add_u32 v117, v117, 4, v112
	v_cvt_pk_bf16_f32 v96, v96, v97
	v_pk_mul_f32 v[126:127], v[124:125], s[82:83] op_sel_hi:[1,0]
	v_pk_mul_f32 v[108:109], v[108:109], v[120:121]
	v_cndmask_b32_e32 v125, v125, v127, vcc
	v_cndmask_b32_e64 v124, v124, v126, s[6:7]
	v_pk_mul_f32 v[102:103], v[102:103], v[124:125]
	v_pk_mul_f32 v[98:99], v[98:99], v[124:125]
	v_cvt_pk_bf16_f32 v101, v102, v103
	v_cvt_pk_bf16_f32 v97, v98, v99
	v_pk_mul_f32 v[110:111], v[110:111], v[124:125]
	v_pk_mul_f32 v[106:107], v[106:107], v[124:125]
	v_pk_mul_f32 v[104:105], v[104:105], v[120:121]
	ds_write2st64_b64 v117, v[100:101], v[96:97] offset0:16 offset1:24
	v_or_b32_e32 v96, 32, v116
	v_cvt_pk_bf16_f32 v108, v108, v109
	v_cvt_pk_bf16_f32 v109, v110, v111
	v_cvt_pk_bf16_f32 v104, v104, v105
	v_cvt_pk_bf16_f32 v105, v106, v107
	v_ashrrev_i32_e32 v97, 31, v96
	ds_write2st64_b64 v117, v[108:109], v[104:105] offset1:8
	v_lshl_add_u64 v[100:101], v[96:97], 3, s[42:43]
	global_load_dwordx4 v[96:99], v[100:101], off offset:16
	s_nop 0
	global_load_dwordx4 v[100:103], v[100:101], off
	v_mfma_f32_16x16x32_bf16 v[20:23], v[152:155], v[166:169], v[136:139]
	s_waitcnt vmcnt(0)
	v_mov_b32_e32 v104, v101
	v_mov_b32_e32 v105, v102
	v_mov_b32_e32 v101, v103
	v_pk_add_f32 v[100:101], v[104:105], v[100:101]
	v_mfma_f32_16x16x32_bf16 v[16:19], v[152:155], v[198:201], v[162:165]
	v_fma_f32 v100, v100, s80, v114
	v_fma_f32 v101, v101, s80, v114
	v_mul_f32_e32 v102, 0x4b800000, v100
	v_cmp_gt_f32_e64 s[6:7], s28, v100
	v_cmp_gt_f32_e32 vcc, s28, v101
	v_mfma_f32_16x16x32_bf16 v[24:27], v[152:155], v[148:151], v[132:135]
	v_cndmask_b32_e64 v100, v100, v102, s[6:7]
	v_mul_f32_e32 v102, 0x4b800000, v101
	v_cndmask_b32_e32 v101, v101, v102, vcc
	v_rsq_f32_e32 v100, v100
	v_rsq_f32_e32 v101, v101
	v_mfma_f32_16x16x32_bf16 v[12:15], v[202:205], v[8:11], v[0:3]
	v_mul_f32_e64 v102, v100, s82
	v_mul_f32_e64 v103, v101, s82
	v_cndmask_b32_e32 v101, v101, v103, vcc
	v_cndmask_b32_e64 v100, v100, v102, s[6:7]
	v_mov_b32_e32 v102, v97
	v_mov_b32_e32 v103, v98
	v_mov_b32_e32 v97, v99
	v_pk_add_f32 v[96:97], v[102:103], v[96:97]
	v_pk_mul_f32 v[84:85], v[84:85], v[100:101]
	v_pk_fma_f32 v[96:97], v[96:97], s[80:81], v[114:115] op_sel_hi:[1,0,0]
	v_pk_mul_f32 v[80:81], v[80:81], v[100:101]
	v_mul_f32_e32 v98, 0x4b800000, v96
	v_cmp_gt_f32_e64 s[6:7], s28, v96
	v_cmp_gt_f32_e32 vcc, s28, v97
	v_cvt_pk_bf16_f32 v84, v84, v85
	v_cndmask_b32_e64 v96, v96, v98, s[6:7]
	v_mul_f32_e32 v98, 0x4b800000, v97
	v_cndmask_b32_e32 v97, v97, v98, vcc
	v_rsq_f32_e32 v96, v96
	v_rsq_f32_e32 v97, v97
	v_cvt_pk_bf16_f32 v80, v80, v81
	v_pk_mul_f32 v[92:93], v[92:93], v[100:101]
	v_pk_mul_f32 v[88:89], v[88:89], v[100:101]
	v_pk_mul_f32 v[98:99], v[96:97], s[82:83] op_sel_hi:[1,0]
	v_cvt_pk_bf16_f32 v92, v92, v93
	v_cndmask_b32_e32 v97, v97, v99, vcc
	v_cndmask_b32_e64 v96, v96, v98, s[6:7]
	v_bitop3_b32 v98, v170, v171, 4 bitop3:0x36
	v_pk_mul_f32 v[86:87], v[86:87], v[96:97]
	v_pk_mul_f32 v[82:83], v[82:83], v[96:97]
	v_lshl_add_u32 v98, v98, 4, v112
	v_cvt_pk_bf16_f32 v85, v86, v87
	v_cvt_pk_bf16_f32 v81, v82, v83
	v_pk_mul_f32 v[94:95], v[94:95], v[96:97]
	v_pk_mul_f32 v[90:91], v[90:91], v[96:97]
	ds_write2st64_b64 v98, v[84:85], v[80:81] offset0:16 offset1:24
	v_or_b32_e32 v80, 48, v116
	v_cvt_pk_bf16_f32 v93, v94, v95
	v_cvt_pk_bf16_f32 v88, v88, v89
	v_cvt_pk_bf16_f32 v89, v90, v91
	v_ashrrev_i32_e32 v81, 31, v80
	ds_write2st64_b64 v98, v[92:93], v[88:89] offset1:8
	v_lshl_add_u64 v[84:85], v[80:81], 3, s[42:43]
	global_load_dwordx4 v[80:83], v[84:85], off offset:16
	s_nop 0
	global_load_dwordx4 v[84:87], v[84:85], off
	v_mfma_f32_16x16x32_bf16 v[0:3], v[202:205], v[198:201], v[144:147]
	s_waitcnt vmcnt(0)
	v_mov_b32_e32 v88, v85
	v_mov_b32_e32 v89, v86
	v_mov_b32_e32 v85, v87
	v_pk_add_f32 v[84:85], v[88:89], v[84:85]
	v_mfma_f32_16x16x32_bf16 v[8:11], v[202:205], v[148:151], v[4:7]
	v_fma_f32 v84, v84, s80, v114
	v_fma_f32 v85, v85, s80, v114
	v_mul_f32_e32 v86, 0x4b800000, v84
	v_cmp_gt_f32_e64 s[6:7], s28, v84
	v_cmp_gt_f32_e32 vcc, s28, v85
	v_mfma_f32_16x16x32_bf16 v[4:7], v[202:205], v[166:169], v[140:143]
	v_cndmask_b32_e64 v84, v84, v86, s[6:7]
	v_mul_f32_e32 v86, 0x4b800000, v85
	v_cndmask_b32_e32 v85, v85, v86, vcc
	v_rsq_f32_e32 v84, v84
	v_rsq_f32_e32 v85, v85
	s_nop 0
	v_pk_mul_f32 v[86:87], v[84:85], s[82:83] op_sel_hi:[1,0]
	s_nop 0
	v_cndmask_b32_e32 v85, v85, v87, vcc
	v_cndmask_b32_e64 v84, v84, v86, s[6:7]
	v_mov_b32_e32 v86, v81
	v_mov_b32_e32 v87, v82
	v_mov_b32_e32 v81, v83
	v_pk_add_f32 v[80:81], v[86:87], v[80:81]
	v_pk_mul_f32 v[68:69], v[68:69], v[84:85]
	v_pk_fma_f32 v[80:81], v[80:81], s[80:81], v[114:115] op_sel_hi:[1,0,0]
	v_pk_mul_f32 v[64:65], v[64:65], v[84:85]
	v_mul_f32_e32 v82, 0x4b800000, v80
	v_cmp_gt_f32_e64 s[6:7], s28, v80
	v_cmp_gt_f32_e32 vcc, s28, v81
	v_cvt_pk_bf16_f32 v68, v68, v69
	v_cndmask_b32_e64 v80, v80, v82, s[6:7]
	v_mul_f32_e32 v82, 0x4b800000, v81
	v_cndmask_b32_e32 v81, v81, v82, vcc
	v_rsq_f32_e32 v80, v80
	v_rsq_f32_e32 v81, v81
	v_cvt_pk_bf16_f32 v64, v64, v65
	v_pk_mul_f32 v[76:77], v[76:77], v[84:85]
	v_pk_mul_f32 v[72:73], v[72:73], v[84:85]
	v_pk_mul_f32 v[82:83], v[80:81], s[82:83] op_sel_hi:[1,0]
	v_cvt_pk_bf16_f32 v76, v76, v77
	v_cndmask_b32_e32 v81, v81, v83, vcc
	v_cndmask_b32_e64 v80, v80, v82, s[6:7]
	v_bitop3_b32 v82, v170, v171, 6 bitop3:0x36
	v_pk_mul_f32 v[70:71], v[70:71], v[80:81]
	v_pk_mul_f32 v[66:67], v[66:67], v[80:81]
	v_lshl_add_u32 v82, v82, 4, v112
	v_cvt_pk_bf16_f32 v69, v70, v71
	v_cvt_pk_bf16_f32 v65, v66, v67
	v_pk_mul_f32 v[78:79], v[78:79], v[80:81]
	v_pk_mul_f32 v[74:75], v[74:75], v[80:81]
	ds_write2st64_b64 v82, v[68:69], v[64:65] offset0:16 offset1:24
	v_or_b32_e32 v64, 64, v116
	v_cvt_pk_bf16_f32 v77, v78, v79
	v_cvt_pk_bf16_f32 v72, v72, v73
	v_cvt_pk_bf16_f32 v73, v74, v75
	v_ashrrev_i32_e32 v65, 31, v64
	ds_write2st64_b64 v82, v[76:77], v[72:73] offset1:8
	v_lshl_add_u64 v[68:69], v[64:65], 3, s[42:43]
	global_load_dwordx4 v[64:67], v[68:69], off offset:16
	s_nop 0
	global_load_dwordx4 v[68:71], v[68:69], off
	s_waitcnt vmcnt(0)
	v_mov_b32_e32 v72, v69
	v_mov_b32_e32 v73, v70
	v_mov_b32_e32 v69, v71
	v_pk_add_f32 v[68:69], v[72:73], v[68:69]
	s_nop 0
	v_pk_fma_f32 v[68:69], v[68:69], s[80:81], v[114:115] op_sel_hi:[1,0,0]
	s_nop 0
	v_mul_f32_e32 v70, 0x4b800000, v68
	v_cmp_gt_f32_e64 s[6:7], s28, v68
	v_cmp_gt_f32_e32 vcc, s28, v69
	s_nop 0
	v_cndmask_b32_e64 v68, v68, v70, s[6:7]
	v_mul_f32_e32 v70, 0x4b800000, v69
	v_cndmask_b32_e32 v69, v69, v70, vcc
	v_rsq_f32_e32 v68, v68
	v_rsq_f32_e32 v69, v69
	s_nop 0
	v_pk_mul_f32 v[70:71], v[68:69], s[82:83] op_sel_hi:[1,0]
	s_nop 0
	v_cndmask_b32_e32 v69, v69, v71, vcc
	v_cndmask_b32_e64 v68, v68, v70, s[6:7]
	v_mov_b32_e32 v70, v65
	v_mov_b32_e32 v71, v66
	v_mov_b32_e32 v65, v67
	v_pk_add_f32 v[64:65], v[70:71], v[64:65]
	v_pk_mul_f32 v[52:53], v[52:53], v[68:69]
	v_pk_fma_f32 v[64:65], v[64:65], s[80:81], v[114:115] op_sel_hi:[1,0,0]
	v_pk_mul_f32 v[48:49], v[48:49], v[68:69]
	v_mul_f32_e32 v66, 0x4b800000, v64
	v_cmp_gt_f32_e64 s[6:7], s28, v64
	v_cmp_gt_f32_e32 vcc, s28, v65
	v_cvt_pk_bf16_f32 v52, v52, v53
	v_cndmask_b32_e64 v64, v64, v66, s[6:7]
	v_mul_f32_e32 v66, 0x4b800000, v65
	v_cndmask_b32_e32 v65, v65, v66, vcc
	v_rsq_f32_e32 v64, v64
	v_rsq_f32_e32 v65, v65
	v_cvt_pk_bf16_f32 v48, v48, v49
	v_pk_mul_f32 v[60:61], v[60:61], v[68:69]
	v_pk_mul_f32 v[56:57], v[56:57], v[68:69]
	v_pk_mul_f32 v[66:67], v[64:65], s[82:83] op_sel_hi:[1,0]
	v_cvt_pk_bf16_f32 v60, v60, v61
	v_cndmask_b32_e32 v65, v65, v67, vcc
	v_cndmask_b32_e64 v64, v64, v66, s[6:7]
	v_bitop3_b32 v66, v170, v171, 8 bitop3:0x36
	v_pk_mul_f32 v[54:55], v[54:55], v[64:65]
	v_pk_mul_f32 v[50:51], v[50:51], v[64:65]
	v_lshl_add_u32 v66, v66, 4, v112
	v_cvt_pk_bf16_f32 v53, v54, v55
	v_cvt_pk_bf16_f32 v49, v50, v51
	v_pk_mul_f32 v[62:63], v[62:63], v[64:65]
	v_pk_mul_f32 v[58:59], v[58:59], v[64:65]
	ds_write2st64_b64 v66, v[52:53], v[48:49] offset0:16 offset1:24
	v_or_b32_e32 v48, 0x50, v116
	v_cvt_pk_bf16_f32 v61, v62, v63
	v_cvt_pk_bf16_f32 v56, v56, v57
	v_cvt_pk_bf16_f32 v57, v58, v59
	v_ashrrev_i32_e32 v49, 31, v48
	ds_write2st64_b64 v66, v[60:61], v[56:57] offset1:8
	v_lshl_add_u64 v[52:53], v[48:49], 3, s[42:43]
	global_load_dwordx4 v[48:51], v[52:53], off offset:16
	s_nop 0
	global_load_dwordx4 v[52:55], v[52:53], off
	s_waitcnt vmcnt(0)
	v_mov_b32_e32 v56, v53
	v_mov_b32_e32 v57, v54
	v_mov_b32_e32 v53, v55
	v_pk_add_f32 v[52:53], v[56:57], v[52:53]
	s_nop 0
	v_pk_fma_f32 v[52:53], v[52:53], s[80:81], v[114:115] op_sel_hi:[1,0,0]
	s_nop 0
	v_mul_f32_e32 v54, 0x4b800000, v52
	v_cmp_gt_f32_e64 s[6:7], s28, v52
	v_cmp_gt_f32_e32 vcc, s28, v53
	s_nop 0
	v_cndmask_b32_e64 v52, v52, v54, s[6:7]
	v_mul_f32_e32 v54, 0x4b800000, v53
	v_cndmask_b32_e32 v53, v53, v54, vcc
	v_rsq_f32_e32 v52, v52
	v_rsq_f32_e32 v53, v53
	s_nop 0
	v_pk_mul_f32 v[54:55], v[52:53], s[82:83] op_sel_hi:[1,0]
	s_nop 0
	v_cndmask_b32_e32 v53, v53, v55, vcc
	v_cndmask_b32_e64 v52, v52, v54, s[6:7]
	v_mov_b32_e32 v54, v49
	v_mov_b32_e32 v55, v50
	v_mov_b32_e32 v49, v51
	v_pk_add_f32 v[48:49], v[54:55], v[48:49]
	v_pk_mul_f32 v[36:37], v[36:37], v[52:53]
	v_pk_fma_f32 v[48:49], v[48:49], s[80:81], v[114:115] op_sel_hi:[1,0,0]
	v_pk_mul_f32 v[32:33], v[32:33], v[52:53]
	v_mul_f32_e32 v50, 0x4b800000, v48
	v_cmp_gt_f32_e64 s[6:7], s28, v48
	v_cmp_gt_f32_e32 vcc, s28, v49
	v_cvt_pk_bf16_f32 v36, v36, v37
	v_cndmask_b32_e64 v48, v48, v50, s[6:7]
	v_mul_f32_e32 v50, 0x4b800000, v49
	v_cndmask_b32_e32 v49, v49, v50, vcc
	v_rsq_f32_e32 v48, v48
	v_rsq_f32_e32 v49, v49
	v_cvt_pk_bf16_f32 v32, v32, v33
	v_pk_mul_f32 v[44:45], v[44:45], v[52:53]
	v_pk_mul_f32 v[40:41], v[40:41], v[52:53]
	v_pk_mul_f32 v[50:51], v[48:49], s[82:83] op_sel_hi:[1,0]
	v_cvt_pk_bf16_f32 v44, v44, v45
	v_cndmask_b32_e32 v49, v49, v51, vcc
	v_cndmask_b32_e64 v48, v48, v50, s[6:7]
	v_bitop3_b32 v50, v170, v171, 10 bitop3:0x36
	v_pk_mul_f32 v[38:39], v[38:39], v[48:49]
	v_pk_mul_f32 v[34:35], v[34:35], v[48:49]
	v_lshl_add_u32 v50, v50, 4, v112
	v_cvt_pk_bf16_f32 v37, v38, v39
	v_cvt_pk_bf16_f32 v33, v34, v35
	v_pk_mul_f32 v[46:47], v[46:47], v[48:49]
	v_pk_mul_f32 v[42:43], v[42:43], v[48:49]
	ds_write2st64_b64 v50, v[36:37], v[32:33] offset0:16 offset1:24
	v_or_b32_e32 v32, 0x60, v116
	v_cvt_pk_bf16_f32 v45, v46, v47
	v_cvt_pk_bf16_f32 v40, v40, v41
	v_cvt_pk_bf16_f32 v41, v42, v43
	v_ashrrev_i32_e32 v33, 31, v32
	ds_write2st64_b64 v50, v[44:45], v[40:41] offset1:8
	v_lshl_add_u64 v[36:37], v[32:33], 3, s[42:43]
	global_load_dwordx4 v[32:35], v[36:37], off offset:16
	s_nop 0
	global_load_dwordx4 v[36:39], v[36:37], off
	s_waitcnt vmcnt(0)
	v_mov_b32_e32 v40, v37
	v_mov_b32_e32 v41, v38
	v_mov_b32_e32 v37, v39
	v_pk_add_f32 v[36:37], v[40:41], v[36:37]
	s_nop 0
	v_pk_fma_f32 v[36:37], v[36:37], s[80:81], v[114:115] op_sel_hi:[1,0,0]
	s_nop 0
	v_mul_f32_e32 v38, 0x4b800000, v36
	v_cmp_gt_f32_e64 s[6:7], s28, v36
	v_cmp_gt_f32_e32 vcc, s28, v37
	s_nop 0
	v_cndmask_b32_e64 v36, v36, v38, s[6:7]
	v_mul_f32_e32 v38, 0x4b800000, v37
	v_cndmask_b32_e32 v37, v37, v38, vcc
	v_rsq_f32_e32 v36, v36
	v_rsq_f32_e32 v37, v37
	s_nop 0
	v_pk_mul_f32 v[38:39], v[36:37], s[82:83] op_sel_hi:[1,0]
	s_nop 0
	v_cndmask_b32_e32 v37, v37, v39, vcc
	v_cndmask_b32_e64 v36, v36, v38, s[6:7]
	v_mov_b32_e32 v38, v33
	v_mov_b32_e32 v39, v34
	v_mov_b32_e32 v33, v35
	v_pk_add_f32 v[32:33], v[38:39], v[32:33]
	v_pk_mul_f32 v[20:21], v[20:21], v[36:37]
	v_pk_fma_f32 v[32:33], v[32:33], s[80:81], v[114:115] op_sel_hi:[1,0,0]
	v_pk_mul_f32 v[16:17], v[16:17], v[36:37]
	v_mul_f32_e32 v34, 0x4b800000, v32
	v_cmp_gt_f32_e64 s[6:7], s28, v32
	v_cmp_gt_f32_e32 vcc, s28, v33
	v_cvt_pk_bf16_f32 v20, v20, v21
	v_cndmask_b32_e64 v32, v32, v34, s[6:7]
	v_mul_f32_e32 v34, 0x4b800000, v33
	v_cndmask_b32_e32 v33, v33, v34, vcc
	v_rsq_f32_e32 v32, v32
	v_rsq_f32_e32 v33, v33
	v_cvt_pk_bf16_f32 v16, v16, v17
	v_pk_mul_f32 v[28:29], v[28:29], v[36:37]
	v_pk_mul_f32 v[24:25], v[24:25], v[36:37]
	v_pk_mul_f32 v[34:35], v[32:33], s[82:83] op_sel_hi:[1,0]
	v_cvt_pk_bf16_f32 v28, v28, v29
	v_cndmask_b32_e32 v33, v33, v35, vcc
	v_cndmask_b32_e64 v32, v32, v34, s[6:7]
	v_bitop3_b32 v34, v170, v171, 12 bitop3:0x36
	v_pk_mul_f32 v[22:23], v[22:23], v[32:33]
	v_pk_mul_f32 v[18:19], v[18:19], v[32:33]
	v_lshl_add_u32 v34, v34, 4, v112
	v_cvt_pk_bf16_f32 v21, v22, v23
	v_cvt_pk_bf16_f32 v17, v18, v19
	v_pk_mul_f32 v[30:31], v[30:31], v[32:33]
	v_pk_mul_f32 v[26:27], v[26:27], v[32:33]
	ds_write2st64_b64 v34, v[20:21], v[16:17] offset0:16 offset1:24
	v_or_b32_e32 v16, 0x70, v116
	v_cvt_pk_bf16_f32 v29, v30, v31
	v_cvt_pk_bf16_f32 v24, v24, v25
	v_cvt_pk_bf16_f32 v25, v26, v27
	v_ashrrev_i32_e32 v17, 31, v16
	ds_write2st64_b64 v34, v[28:29], v[24:25] offset1:8
	v_lshl_add_u64 v[20:21], v[16:17], 3, s[42:43]
	global_load_dwordx4 v[16:19], v[20:21], off offset:16
	s_nop 0
	global_load_dwordx4 v[20:23], v[20:21], off
	s_waitcnt vmcnt(0)
	v_mov_b32_e32 v24, v21
	v_mov_b32_e32 v25, v22
	v_mov_b32_e32 v21, v23
	v_pk_add_f32 v[20:21], v[24:25], v[20:21]
	s_nop 0
	v_pk_fma_f32 v[20:21], v[20:21], s[80:81], v[114:115] op_sel_hi:[1,0,0]
	s_nop 0
	v_mul_f32_e32 v22, 0x4b800000, v20
	v_cmp_gt_f32_e64 s[6:7], s28, v20
	v_cmp_gt_f32_e32 vcc, s28, v21
	s_nop 0
	v_cndmask_b32_e64 v20, v20, v22, s[6:7]
	v_mul_f32_e32 v22, 0x4b800000, v21
	v_cndmask_b32_e32 v21, v21, v22, vcc
	v_rsq_f32_e32 v20, v20
	v_rsq_f32_e32 v21, v21
	s_nop 0
	v_pk_mul_f32 v[22:23], v[20:21], s[82:83] op_sel_hi:[1,0]
	s_nop 0
	v_cndmask_b32_e32 v21, v21, v23, vcc
	v_cndmask_b32_e64 v20, v20, v22, s[6:7]
	v_mov_b32_e32 v22, v17
	v_mov_b32_e32 v23, v18
	v_mov_b32_e32 v17, v19
	v_pk_add_f32 v[16:17], v[22:23], v[16:17]
	v_pk_mul_f32 v[0:1], v[0:1], v[20:21]
	v_pk_fma_f32 v[16:17], v[16:17], s[80:81], v[114:115] op_sel_hi:[1,0,0]
	v_pk_mul_f32 v[12:13], v[12:13], v[20:21]
	v_mul_f32_e32 v18, 0x4b800000, v16
	v_cmp_gt_f32_e64 s[6:7], s28, v16
	v_cmp_gt_f32_e32 vcc, s28, v17
	v_pk_mul_f32 v[8:9], v[8:9], v[20:21]
	v_cndmask_b32_e64 v16, v16, v18, s[6:7]
	v_mul_f32_e32 v18, 0x4b800000, v17
	v_cndmask_b32_e32 v17, v17, v18, vcc
	v_rsq_f32_e32 v16, v16
	v_rsq_f32_e32 v17, v17
	v_cvt_pk_bf16_f32 v0, v0, v1
	v_cvt_pk_bf16_f32 v12, v12, v13
	v_cvt_pk_bf16_f32 v8, v8, v9
	v_pk_mul_f32 v[18:19], v[16:17], s[82:83] op_sel_hi:[1,0]
	v_pk_mul_f32 v[4:5], v[4:5], v[20:21]
	v_cndmask_b32_e32 v17, v17, v19, vcc
	v_cndmask_b32_e64 v16, v16, v18, s[6:7]
	v_pk_mul_f32 v[2:3], v[2:3], v[16:17]
	v_bitop3_b32 v18, v170, v171, 14 bitop3:0x36
	v_pk_mul_f32 v[14:15], v[14:15], v[16:17]
	v_pk_mul_f32 v[10:11], v[10:11], v[16:17]
	v_cvt_pk_bf16_f32 v1, v2, v3
	v_xor_b32_e32 v3, v123, v119
	v_lshl_add_u32 v18, v18, 4, v112
	v_cvt_pk_bf16_f32 v13, v14, v15
	v_cvt_pk_bf16_f32 v9, v10, v11
	v_lshlrev_b32_e32 v3, 4, v3
	ds_write2st64_b64 v18, v[12:13], v[8:9] offset1:8
	v_pk_mul_f32 v[6:7], v[6:7], v[16:17]
	v_lshlrev_b32_e32 v2, 8, v123
	v_and_b32_e32 v8, 0xf0, v3
	v_cvt_pk_bf16_f32 v4, v4, v5
	v_cvt_pk_bf16_f32 v5, v6, v7
	s_and_b32 s6, s8, 0xf80
	v_add3_u32 v2, s78, v2, v8
	ds_write2st64_b64 v18, v[4:5], v[0:1] offset0:16 offset1:24
	s_lshl_b32 s6, s6, 1
	ds_read_b128 v[2:5], v2
	s_add_u32 s4, s4, s6
	v_lshlrev_b32_e32 v0, 4, v119
	s_addc_u32 s5, s5, 0
	v_and_b32_e32 v112, 0xf0, v0
	v_lshl_add_u64 v[0:1], s[4:5], 0, v[112:113]
	v_lshlrev_b32_e32 v112, 13, v123
	v_lshl_add_u64 v[6:7], v[0:1], 0, v[112:113]
	s_waitcnt lgkmcnt(0)
	global_store_dwordx4 v[6:7], v[2:5], off
	v_or_b32_e32 v6, 4, v123
	v_lshlrev_b32_e32 v112, 13, v6
	v_bitop3_b32 v3, v123, v119, 4 bitop3:0x36
	v_lshlrev_b32_e32 v3, 4, v3
	v_lshlrev_b32_e32 v2, 8, v6
	v_and_b32_e32 v3, 0xf0, v3
	v_add3_u32 v2, s78, v2, v3
	ds_read_b128 v[2:5], v2
	v_lshl_add_u64 v[6:7], v[0:1], 0, v[112:113]
	s_mov_b64 s[4:5], 0
	s_waitcnt lgkmcnt(0)
	global_store_dwordx4 v[6:7], v[2:5], off
	s_nop 1
	v_bitop3_b32 v3, v123, v119, 8 bitop3:0x36
	v_or_b32_e32 v6, 8, v123
	v_lshlrev_b32_e32 v3, 4, v3
	v_lshlrev_b32_e32 v2, 8, v6
	v_and_b32_e32 v3, 0xf0, v3
	v_add3_u32 v2, s78, v2, v3
	ds_read_b128 v[2:5], v2
	v_lshlrev_b32_e32 v112, 13, v6
	v_lshl_add_u64 v[6:7], v[0:1], 0, v[112:113]
	s_waitcnt lgkmcnt(0)
	global_store_dwordx4 v[6:7], v[2:5], off
	s_nop 1
	v_bitop3_b32 v3, v123, v119, 12 bitop3:0x36
	v_or_b32_e32 v6, 12, v123
	v_lshlrev_b32_e32 v3, 4, v3
	v_lshlrev_b32_e32 v2, 8, v6
	v_and_b32_e32 v3, 0xf0, v3
	v_add3_u32 v2, s78, v2, v3
	ds_read_b128 v[2:5], v2
	v_lshlrev_b32_e32 v112, 13, v6
	v_lshl_add_u64 v[6:7], v[0:1], 0, v[112:113]
	s_waitcnt lgkmcnt(0)
	global_store_dwordx4 v[6:7], v[2:5], off
	v_or_b32_e32 v6, 16, v123
	s_nop 0
	v_lshlrev_b32_e32 v2, 8, v6
	v_add3_u32 v2, s78, v2, v8
	ds_read_b128 v[2:5], v2
	v_lshlrev_b32_e32 v112, 13, v6
	v_lshl_add_u64 v[6:7], v[0:1], 0, v[112:113]
	s_waitcnt lgkmcnt(0)
	global_store_dwordx4 v[6:7], v[2:5], off
	s_nop 1
	v_bitop3_b32 v3, v123, v119, 20 bitop3:0x36
	v_or_b32_e32 v6, 20, v123
	v_lshlrev_b32_e32 v3, 4, v3
	v_lshlrev_b32_e32 v2, 8, v6
	v_and_b32_e32 v3, 0xf0, v3
	v_add3_u32 v2, s78, v2, v3
	ds_read_b128 v[2:5], v2
	v_lshlrev_b32_e32 v112, 13, v6
	v_lshl_add_u64 v[6:7], v[0:1], 0, v[112:113]
	s_waitcnt lgkmcnt(0)
	global_store_dwordx4 v[6:7], v[2:5], off
	s_nop 1
	v_bitop3_b32 v3, v123, v119, 24 bitop3:0x36
	v_or_b32_e32 v6, 24, v123
	v_lshlrev_b32_e32 v3, 4, v3
	v_lshlrev_b32_e32 v2, 8, v6
	v_and_b32_e32 v3, 0xf0, v3
	v_add3_u32 v2, s78, v2, v3
	ds_read_b128 v[2:5], v2
	v_lshlrev_b32_e32 v112, 13, v6
	v_lshl_add_u64 v[6:7], v[0:1], 0, v[112:113]
	s_waitcnt lgkmcnt(0)
	global_store_dwordx4 v[6:7], v[2:5], off
	s_nop 1
	v_bitop3_b32 v3, v123, v119, 28 bitop3:0x36
	v_or_b32_e32 v6, 28, v123
	v_lshlrev_b32_e32 v3, 4, v3
	v_lshlrev_b32_e32 v2, 8, v6
	v_and_b32_e32 v3, 0xf0, v3
	v_add3_u32 v2, s78, v2, v3
	ds_read_b128 v[2:5], v2
	v_lshlrev_b32_e32 v112, 13, v6
	v_lshl_add_u64 v[6:7], v[0:1], 0, v[112:113]
	s_waitcnt lgkmcnt(0)
	global_store_dwordx4 v[6:7], v[2:5], off
	v_or_b32_e32 v6, 32, v123
	s_nop 0
	v_lshlrev_b32_e32 v2, 8, v6
	v_add3_u32 v2, s78, v2, v8
	ds_read_b128 v[2:5], v2
	v_lshlrev_b32_e32 v112, 13, v6
	v_lshl_add_u64 v[6:7], v[0:1], 0, v[112:113]
	s_waitcnt lgkmcnt(0)
	global_store_dwordx4 v[6:7], v[2:5], off
	s_nop 1
	v_bitop3_b32 v3, v123, v119, 36 bitop3:0x36
	v_or_b32_e32 v6, 36, v123
	v_lshlrev_b32_e32 v3, 4, v3
	v_lshlrev_b32_e32 v2, 8, v6
	v_and_b32_e32 v3, 0xf0, v3
	v_add3_u32 v2, s78, v2, v3
	ds_read_b128 v[2:5], v2
	v_lshlrev_b32_e32 v112, 13, v6
	v_lshl_add_u64 v[6:7], v[0:1], 0, v[112:113]
	s_waitcnt lgkmcnt(0)
	global_store_dwordx4 v[6:7], v[2:5], off
	s_nop 1
	v_bitop3_b32 v3, v123, v119, 40 bitop3:0x36
	v_or_b32_e32 v6, 40, v123
	v_lshlrev_b32_e32 v3, 4, v3
	v_lshlrev_b32_e32 v2, 8, v6
	v_and_b32_e32 v3, 0xf0, v3
	v_add3_u32 v2, s78, v2, v3
	ds_read_b128 v[2:5], v2
	v_lshlrev_b32_e32 v112, 13, v6
	v_lshl_add_u64 v[6:7], v[0:1], 0, v[112:113]
	s_waitcnt lgkmcnt(0)
	global_store_dwordx4 v[6:7], v[2:5], off
	s_nop 1
	v_bitop3_b32 v3, v123, v119, 44 bitop3:0x36
	v_or_b32_e32 v6, 44, v123
	v_lshlrev_b32_e32 v3, 4, v3
	v_lshlrev_b32_e32 v2, 8, v6
	v_and_b32_e32 v3, 0xf0, v3
	v_add3_u32 v2, s78, v2, v3
	ds_read_b128 v[2:5], v2
	v_lshlrev_b32_e32 v112, 13, v6
	v_lshl_add_u64 v[6:7], v[0:1], 0, v[112:113]
	s_waitcnt lgkmcnt(0)
	global_store_dwordx4 v[6:7], v[2:5], off
	v_or_b32_e32 v6, 48, v123
	s_nop 0
	v_lshlrev_b32_e32 v2, 8, v6
	v_add3_u32 v2, s78, v2, v8
	ds_read_b128 v[2:5], v2
	v_lshlrev_b32_e32 v112, 13, v6
	v_lshl_add_u64 v[6:7], v[0:1], 0, v[112:113]
	s_waitcnt lgkmcnt(0)
	global_store_dwordx4 v[6:7], v[2:5], off
	s_nop 1
	v_bitop3_b32 v3, v123, v119, 52 bitop3:0x36
	v_or_b32_e32 v6, 52, v123
	v_lshlrev_b32_e32 v3, 4, v3
	v_lshlrev_b32_e32 v2, 8, v6
	v_and_b32_e32 v3, 0xf0, v3
	v_add3_u32 v2, s78, v2, v3
	ds_read_b128 v[2:5], v2
	v_lshlrev_b32_e32 v112, 13, v6
	v_lshl_add_u64 v[6:7], v[0:1], 0, v[112:113]
	s_waitcnt lgkmcnt(0)
	global_store_dwordx4 v[6:7], v[2:5], off
	s_nop 1
	v_bitop3_b32 v3, v123, v119, 56 bitop3:0x36
	v_or_b32_e32 v6, 56, v123
	v_lshlrev_b32_e32 v3, 4, v3
	v_lshlrev_b32_e32 v2, 8, v6
	v_and_b32_e32 v3, 0xf0, v3
	v_add3_u32 v2, s78, v2, v3
	ds_read_b128 v[2:5], v2
	v_lshlrev_b32_e32 v112, 13, v6
	v_lshl_add_u64 v[6:7], v[0:1], 0, v[112:113]
	s_waitcnt lgkmcnt(0)
	global_store_dwordx4 v[6:7], v[2:5], off
	s_nop 1
	v_bitop3_b32 v4, v123, v119, 60 bitop3:0x36
	v_or_b32_e32 v3, 60, v123
	v_lshlrev_b32_e32 v4, 4, v4
	v_lshlrev_b32_e32 v2, 8, v3
	v_and_b32_e32 v4, 0xf0, v4
	v_add3_u32 v2, s78, v2, v4
	v_lshlrev_b32_e32 v112, 12, v3

.LBB0_804:
	s_and_b32 s4, s37, 7
	s_lshl_b32 s4, s4, s14
	s_ashr_i32 s5, s37, 3
	s_add_i32 s4, s4, s5
	s_abs_i32 s8, s4
	s_mul_hi_u32 s9, s8, s19
	s_mul_i32 s10, s9, s6
	s_sub_i32 s8, s8, s10
	s_ashr_i32 s5, s4, 31
	s_add_i32 s10, s9, 1
	s_sub_i32 s11, s8, s6
	s_cmp_ge_u32 s8, s6
	s_cselect_b32 s9, s10, s9
	s_cselect_b32 s8, s11, s8
	s_add_i32 s10, s9, 1
	s_cmp_ge_u32 s8, s6
	s_cselect_b32 s8, s10, s9
	s_xor_b32 s8, s8, s5
	s_sub_i32 s39, s8, s5
	s_mul_i32 s5, s39, s6
	v_mov_b32_e32 v158, v157
	s_sub_i32 s4, s4, s5
	s_lshl_b32 s41, s39, 8
	v_readfirstlane_b32 s5, v158
	s_ashr_i32 s8, s5, 1
	s_and_b32 s8, s8, 0xffffff80
	s_add_i32 s12, s8, s41
	s_and_b32 s8, s5, 0xc0
	s_lshl_b32 s5, s5, 8
	s_ashr_i32 s9, s4, 2
	s_lshl_b32 s42, s4, 8
	s_and_b32 s38, s5, 0xffffc000
	s_add_i32 s10, s9, 2
	s_and_b64 s[4:5], s[90:91], exec
	s_cselect_b32 s13, s9, s10
	s_and_b32 s4, s42, 0x300
	s_or_b32 s40, s8, s4
	v_and_b32_e32 v138, 63, v158
	v_and_b32_e32 v140, 15, v158
	v_bfe_u32 v139, v158, 4, 2
	s_cmp_eq_u32 s13, 1
	s_mov_b64 s[4:5], -1
	s_cbranch_scc1 .LBB0_872
	v_or_b32_e32 v0, s12, v140
	v_ashrrev_i32_e32 v1, 31, v0
	v_lshl_add_u64 v[0:1], v[0:1], 2, s[62:63]
	v_mov_b32_e32 v10, v157
	global_load_dword v159, v[0:1], off
	global_load_dword v147, v[0:1], off offset:64
	global_load_dword v146, v[0:1], off offset:128
	global_load_dword v145, v[0:1], off offset:192
	global_load_dword v144, v[0:1], off offset:256
	global_load_dword v143, v[0:1], off offset:320
	global_load_dword v142, v[0:1], off offset:384
	global_load_dword v141, v[0:1], off offset:448
	s_add_i32 s45, s42, 0xffffff00
	v_readfirstlane_b32 s43, v10
	s_ashr_i32 s44, s43, 6
	s_lshl_b32 s30, s44, 2
	s_cmp_lt_i32 s44, 4
	s_cselect_b64 s[4:5], -1, 0
	s_and_b32 s46, s43, 0xffffffc0
	s_and_b64 s[8:9], s[4:5], exec
	s_cselect_b32 s8, s41, s45
	s_add_i32 s8, s8, s46
	s_and_b64 s[4:5], s[4:5], exec
	s_cselect_b32 s10, s57, s18
	s_cselect_b32 s11, s56, s15
	s_ashr_i32 s9, s8, 31
	s_lshl_b64 s[4:5], s[8:9], 11
	s_add_u32 s8, s11, s4
	s_addc_u32 s9, s10, s5
	s_or_b32 s10, s30, 1
	s_cmp_lt_i32 s10, 16
	s_cselect_b64 s[4:5], -1, 0
	s_lshl_b32 s28, s10, 4
	s_and_b64 s[10:11], s[4:5], exec
	s_cselect_b32 s47, s41, s45
	s_add_i32 s10, s47, s28
	s_and_b64 s[4:5], s[4:5], exec
	s_cselect_b32 s48, s57, s18
	s_cselect_b32 s49, s56, s15
	s_ashr_i32 s11, s10, 31
	s_lshl_b64 s[4:5], s[10:11], 11
	s_add_u32 s10, s49, s4
	s_addc_u32 s11, s48, s5
	s_or_b32 s28, s30, 2
	s_cmp_lt_i32 s28, 16
	s_cselect_b64 s[4:5], -1, 0
	s_lshl_b32 s31, s28, 4
	s_and_b64 s[28:29], s[4:5], exec
	s_cselect_b32 s50, s41, s45
	s_add_i32 s28, s50, s31
	s_and_b64 s[4:5], s[4:5], exec
	s_cselect_b32 s51, s57, s18
	s_cselect_b32 s66, s56, s15
	s_ashr_i32 s29, s28, 31
	s_lshl_b64 s[4:5], s[28:29], 11
	s_add_u32 s28, s66, s4
	s_addc_u32 s29, s51, s5
	s_or_b32 s30, s30, 3
	s_cmp_lt_i32 s30, 16
	s_cselect_b64 s[4:5], -1, 0
	s_lshl_b32 s67, s30, 4
	s_and_b64 s[30:31], s[4:5], exec
	s_cselect_b32 s45, s41, s45
	s_add_i32 s30, s45, s67
	s_and_b64 s[4:5], s[4:5], exec
	v_lshrrev_b32_e32 v11, 4, v10
	s_cselect_b32 s67, s57, s18
	s_cselect_b32 s83, s56, s15
	s_ashr_i32 s31, s30, 31
	v_sub_u32_e32 v1, 0, v11
	s_lshl_b64 s[4:5], s[30:31], 11
	v_lshlrev_b32_e32 v0, 9, v10
	v_xor_b32_e32 v1, v10, v1
	s_add_u32 s30, s83, s4
	v_and_b32_e32 v0, 0x7800, v0
	v_lshlrev_b32_e32 v1, 4, v1
	s_addc_u32 s31, s67, s5
	s_lshl_b32 s4, s44, 12
	v_and_or_b32 v128, v1, 48, v0
	s_mov_b32 m0, s4
	v_lshl_add_u64 v[0:1], s[8:9], 0, v[128:129]
	global_load_lds_dwordx4 v128, s[8:9]
	s_or_b32 m0, s4, 0x400
	v_lshl_add_u64 v[2:3], s[10:11], 0, v[128:129]
	global_load_lds_dwordx4 v128, s[10:11]
	s_or_b32 m0, s4, 0x800
	v_lshl_add_u64 v[8:9], v[0:1], 0, 64
	global_load_lds_dwordx4 v128, s[28:29]
	s_or_b32 m0, s4, 0xc00
	v_lshl_add_u64 v[4:5], s[28:29], 0, v[128:129]
	global_load_lds_dwordx4 v128, s[30:31]
	s_add_i32 m0, s4, 0x8000
	v_lshl_add_u64 v[6:7], s[30:31], 0, v[128:129]
	global_load_lds_dwordx4 v[8:9], off
	v_lshl_add_u64 v[8:9], v[2:3], 0, 64
	s_add_i32 m0, s4, 0x8400
	v_lshl_add_u64 v[2:3], v[2:3], 0, s[88:89]
	global_load_lds_dwordx4 v[8:9], off
	v_lshl_add_u64 v[8:9], v[4:5], 0, 64
	s_add_i32 m0, s4, 0x8800
	s_lshr_b32 s5, s43, 1
	global_load_lds_dwordx4 v[8:9], off
	v_lshl_add_u64 v[8:9], v[6:7], 0, 64
	s_add_i32 m0, s4, 0x8c00
	s_add_i32 s8, s45, s46
	global_load_lds_dwordx4 v[8:9], off
	s_add_i32 m0, s4, 0x10000
	v_lshl_add_u64 v[8:9], v[0:1], 0, s[88:89]
	global_load_lds_dwordx4 v[8:9], off
	s_add_i32 m0, s4, 0x10400
	v_and_b32_e32 v12, 15, v10
	global_load_lds_dwordx4 v[2:3], off
	v_lshl_add_u64 v[2:3], v[4:5], 0, s[88:89]
	s_add_i32 m0, s4, 0x10800
	s_and_b32 s5, s5, 0x3ffff80
	global_load_lds_dwordx4 v[2:3], off
	v_lshl_add_u64 v[2:3], v[6:7], 0, s[88:89]
	s_add_i32 m0, s4, 0x10c00
	s_ashr_i32 s9, s8, 31
	global_load_lds_dwordx4 v[2:3], off
	v_lshrrev_b32_e32 v2, 2, v10
	v_sub_u32_e32 v2, 0, v2
	v_bitop3_b32 v2, v11, 3, v2 bitop3:0x48
	v_or_b32_e32 v3, s5, v12
	v_lshlrev_b32_e32 v2, 4, v2
	s_and_b32 s5, s43, 0xc0
	s_lshl_b64 s[8:9], s[8:9], 11
	v_lshl_or_b32 v160, v3, 6, v2
	v_or_b32_e32 v3, s5, v12
	s_add_u32 s8, s83, s8
	v_lshlrev_b32_e32 v3, 6, v3
	s_addc_u32 s9, s67, s9
	v_or3_b32 v161, v2, v3, s68
	v_lshl_add_u64 v[2:3], s[8:9], 0, v[128:129]
	s_add_i32 s8, s50, s46
	s_ashr_i32 s9, s8, 31
	s_lshl_b64 s[8:9], s[8:9], 11
	s_add_u32 s8, s66, s8
	s_addc_u32 s9, s51, s9
	v_lshl_add_u64 v[130:131], v[2:3], 0, s[92:93]
	v_lshl_add_u64 v[2:3], s[8:9], 0, v[128:129]
	s_add_i32 s8, s47, s46
	s_ashr_i32 s9, s8, 31
	s_lshl_b64 s[8:9], s[8:9], 11
	s_add_u32 s8, s49, s8
	s_addc_u32 s9, s48, s9
	v_lshl_add_u64 v[132:133], v[2:3], 0, s[94:95]
	v_lshl_add_u64 v[2:3], s[8:9], 0, v[128:129]
	v_lshl_add_u64 v[136:137], v[0:1], 0, s[78:79]
	v_mov_b32_e32 v0, 0
	v_lshl_add_u64 v[134:135], v[2:3], 0, s[96:97]
	s_mov_b32 s5, 0x18000
	v_mov_b32_e32 v1, v0
	v_mov_b32_e32 v2, v0
	v_mov_b32_e32 v3, v0
	v_mov_b32_e32 v4, v0
	v_mov_b32_e32 v5, v0
	v_mov_b32_e32 v6, v0
	v_mov_b32_e32 v7, v0
	v_mov_b32_e32 v8, v0
	v_mov_b32_e32 v9, v0
	v_mov_b32_e32 v10, v0
	v_mov_b32_e32 v11, v0
	v_mov_b32_e32 v12, v0
	v_mov_b32_e32 v13, v0
	v_mov_b32_e32 v14, v0
	v_mov_b32_e32 v15, v0
	v_mov_b32_e32 v16, v0
	v_mov_b32_e32 v17, v0
	v_mov_b32_e32 v18, v0
	v_mov_b32_e32 v19, v0
	v_mov_b32_e32 v20, v0
	v_mov_b32_e32 v21, v0
	v_mov_b32_e32 v22, v0
	v_mov_b32_e32 v23, v0
	v_mov_b32_e32 v24, v0
	v_mov_b32_e32 v25, v0
	v_mov_b32_e32 v26, v0
	v_mov_b32_e32 v27, v0
	v_mov_b32_e32 v28, v0
	v_mov_b32_e32 v29, v0
	v_mov_b32_e32 v30, v0
	v_mov_b32_e32 v31, v0
	v_mov_b32_e32 v32, v0
	v_mov_b32_e32 v33, v0
	v_mov_b32_e32 v34, v0
	v_mov_b32_e32 v35, v0
	v_mov_b32_e32 v36, v0
	v_mov_b32_e32 v37, v0
	v_mov_b32_e32 v38, v0
	v_mov_b32_e32 v39, v0
	v_mov_b32_e32 v40, v0
	v_mov_b32_e32 v41, v0
	v_mov_b32_e32 v42, v0
	v_mov_b32_e32 v43, v0
	v_mov_b32_e32 v44, v0
	v_mov_b32_e32 v45, v0
	v_mov_b32_e32 v46, v0
	v_mov_b32_e32 v47, v0
	v_mov_b32_e32 v48, v0
	v_mov_b32_e32 v49, v0
	v_mov_b32_e32 v50, v0
	v_mov_b32_e32 v51, v0
	v_mov_b32_e32 v52, v0
	v_mov_b32_e32 v53, v0
	v_mov_b32_e32 v54, v0
	v_mov_b32_e32 v55, v0
	v_mov_b32_e32 v56, v0
	v_mov_b32_e32 v57, v0
	v_mov_b32_e32 v58, v0
	v_mov_b32_e32 v59, v0
	v_mov_b32_e32 v60, v0
	v_mov_b32_e32 v61, v0
	v_mov_b32_e32 v62, v0
	v_mov_b32_e32 v63, v0
	v_mov_b32_e32 v64, v0
	v_mov_b32_e32 v65, v0
	v_mov_b32_e32 v66, v0
	v_mov_b32_e32 v67, v0
	v_mov_b32_e32 v68, v0
	v_mov_b32_e32 v69, v0
	v_mov_b32_e32 v70, v0
	v_mov_b32_e32 v71, v0
	v_mov_b32_e32 v72, v0
	v_mov_b32_e32 v73, v0
	v_mov_b32_e32 v74, v0
	v_mov_b32_e32 v75, v0
	v_mov_b32_e32 v76, v0
	v_mov_b32_e32 v77, v0
	v_mov_b32_e32 v78, v0
	v_mov_b32_e32 v79, v0
	v_mov_b32_e32 v80, v0
	v_mov_b32_e32 v81, v0
	v_mov_b32_e32 v82, v0
	v_mov_b32_e32 v83, v0
	v_mov_b32_e32 v84, v0
	v_mov_b32_e32 v85, v0
	v_mov_b32_e32 v86, v0
	v_mov_b32_e32 v87, v0
	v_mov_b32_e32 v88, v0
	v_mov_b32_e32 v89, v0
	v_mov_b32_e32 v90, v0
	v_mov_b32_e32 v91, v0
	v_mov_b32_e32 v92, v0
	v_mov_b32_e32 v93, v0
	v_mov_b32_e32 v94, v0
	v_mov_b32_e32 v95, v0
	v_mov_b32_e32 v96, v0
	v_mov_b32_e32 v97, v0
	v_mov_b32_e32 v98, v0
	v_mov_b32_e32 v99, v0
	v_mov_b32_e32 v100, v0
	v_mov_b32_e32 v101, v0
	v_mov_b32_e32 v102, v0
	v_mov_b32_e32 v103, v0
	v_mov_b32_e32 v104, v0
	v_mov_b32_e32 v105, v0
	v_mov_b32_e32 v106, v0
	v_mov_b32_e32 v107, v0
	v_mov_b32_e32 v108, v0
	v_mov_b32_e32 v109, v0
	v_mov_b32_e32 v110, v0
	v_mov_b32_e32 v111, v0
	v_mov_b32_e32 v112, v0
	v_mov_b32_e32 v113, v0
	v_mov_b32_e32 v114, v0
	v_mov_b32_e32 v115, v0
	v_mov_b32_e32 v116, v0
	v_mov_b32_e32 v117, v0
	v_mov_b32_e32 v118, v0
	v_mov_b32_e32 v119, v0
	v_mov_b32_e32 v120, v0
	v_mov_b32_e32 v121, v0
	v_mov_b32_e32 v122, v0
	v_mov_b32_e32 v123, v0
	v_mov_b32_e32 v124, v0
	v_mov_b32_e32 v125, v0
	v_mov_b32_e32 v126, v0
	v_mov_b32_e32 v127, v0
	s_add_i32 s8, s5, 0xfffe8000
	s_and_b32 s9, s5, 0x18000
	s_waitcnt vmcnt(8)
	s_barrier
	s_and_b32 s8, s8, 0x18000
	s_add_i32 s9, s4, s9
	v_add_u32_e32 v128, s8, v160
	v_or_b32_e32 v170, s8, v161
	s_add_i32 s11, s9, 0x400
	s_add_i32 s10, s9, 0x800
	s_add_i32 s8, s9, 0xc00
	s_add_i32 s5, s5, 0x8000
	s_cmp_eq_u32 s5, 0x100000
	ds_read_b128 v[182:185], v128
	ds_read_b128 v[162:165], v170
	ds_read_b128 v[166:169], v170 offset:1024
	ds_read_b128 v[174:177], v170 offset:2048
	ds_read_b128 v[178:181], v170 offset:3072
	ds_read_b128 v[186:189], v128 offset:1024
	ds_read_b128 v[190:193], v128 offset:2048
	ds_read_b128 v[194:197], v128 offset:3072
	ds_read_b128 v[232:235], v128 offset:4096
	ds_read_b128 v[236:239], v128 offset:5120
	ds_read_b128 v[240:243], v128 offset:6144
	ds_read_b128 v[244:247], v128 offset:7168
	s_mov_b32 m0, s9
	s_nop 0
	global_load_lds_dwordx4 v[136:137], off
	v_lshl_add_u64 v[136:137], v[136:137], 0, 64
	s_mov_b32 m0, s11
	s_nop 0
	global_load_lds_dwordx4 v[134:135], off
	v_lshl_add_u64 v[134:135], v[134:135], 0, 64
	s_mov_b32 m0, s10
	s_nop 0
	global_load_lds_dwordx4 v[132:133], off
	v_lshl_add_u64 v[132:133], v[132:133], 0, 64
	s_mov_b32 m0, s8
	s_nop 0
	global_load_lds_dwordx4 v[130:131], off
	v_lshl_add_u64 v[130:131], v[130:131], 0, 64
	s_waitcnt lgkmcnt(4)
	v_mfma_f32_16x16x32_bf16 v[124:127], v[162:165], v[182:185], v[124:127]
	v_mfma_f32_16x16x32_bf16 v[120:123], v[166:169], v[182:185], v[120:123]
	v_mfma_f32_16x16x32_bf16 v[116:119], v[174:177], v[182:185], v[116:119]
	v_mfma_f32_16x16x32_bf16 v[112:115], v[178:181], v[182:185], v[112:115]
	v_mfma_f32_16x16x32_bf16 v[108:111], v[162:165], v[186:189], v[108:111]
	v_mfma_f32_16x16x32_bf16 v[104:107], v[166:169], v[186:189], v[104:107]
	v_mfma_f32_16x16x32_bf16 v[100:103], v[174:177], v[186:189], v[100:103]
	v_mfma_f32_16x16x32_bf16 v[96:99], v[178:181], v[186:189], v[96:99]
	v_mfma_f32_16x16x32_bf16 v[92:95], v[162:165], v[190:193], v[92:95]
	v_mfma_f32_16x16x32_bf16 v[88:91], v[166:169], v[190:193], v[88:91]
	v_mfma_f32_16x16x32_bf16 v[84:87], v[174:177], v[190:193], v[84:87]
	v_mfma_f32_16x16x32_bf16 v[80:83], v[178:181], v[190:193], v[80:83]
	v_mfma_f32_16x16x32_bf16 v[76:79], v[162:165], v[194:197], v[76:79]
	v_mfma_f32_16x16x32_bf16 v[72:75], v[166:169], v[194:197], v[72:75]
	v_mfma_f32_16x16x32_bf16 v[68:71], v[174:177], v[194:197], v[68:71]
	v_mfma_f32_16x16x32_bf16 v[64:67], v[178:181], v[194:197], v[64:67]

.LBB0_872:
	s_and_b64 vcc, exec, s[4:5]
	s_cbranch_vccz .LBB0_803
	v_mov_b32_e32 v10, v157
	s_addk_i32 s42, 0xff00
	v_readfirstlane_b32 s13, v10
	s_ashr_i32 s43, s13, 6
	s_lshl_b32 s30, s43, 2
	s_cmp_lt_i32 s43, 4
	s_cselect_b64 s[4:5], -1, 0
	s_and_b32 s44, s13, 0xffffffc0
	s_and_b64 s[8:9], s[4:5], exec
	s_cselect_b32 s8, s41, s42
	s_add_i32 s8, s8, s44
	s_and_b64 s[4:5], s[4:5], exec
	s_cselect_b32 s10, s57, s18
	s_cselect_b32 s11, s56, s15
	s_ashr_i32 s9, s8, 31
	s_lshl_b64 s[4:5], s[8:9], 11
	s_add_u32 s8, s11, s4
	s_addc_u32 s9, s10, s5
	s_or_b32 s10, s30, 1
	s_cmp_lt_i32 s10, 16
	s_cselect_b64 s[4:5], -1, 0
	s_lshl_b32 s28, s10, 4
	s_and_b64 s[10:11], s[4:5], exec
	s_cselect_b32 s45, s41, s42
	s_add_i32 s10, s45, s28
	s_and_b64 s[4:5], s[4:5], exec
	s_cselect_b32 s46, s57, s18
	s_cselect_b32 s47, s56, s15
	s_ashr_i32 s11, s10, 31
	s_lshl_b64 s[4:5], s[10:11], 11
	s_add_u32 s10, s47, s4
	s_addc_u32 s11, s46, s5
	s_or_b32 s28, s30, 2
	s_cmp_lt_i32 s28, 16
	s_cselect_b64 s[4:5], -1, 0
	s_lshl_b32 s31, s28, 4
	s_and_b64 s[28:29], s[4:5], exec
	s_cselect_b32 s48, s41, s42
	s_add_i32 s28, s48, s31
	s_and_b64 s[4:5], s[4:5], exec
	s_cselect_b32 s49, s57, s18
	s_cselect_b32 s50, s56, s15
	s_ashr_i32 s29, s28, 31
	s_lshl_b64 s[4:5], s[28:29], 11
	s_add_u32 s28, s50, s4
	s_addc_u32 s29, s49, s5
	s_or_b32 s30, s30, 3
	s_cmp_lt_i32 s30, 16
	s_cselect_b64 s[4:5], -1, 0
	s_lshl_b32 s51, s30, 4
	s_and_b64 s[30:31], s[4:5], exec
	s_cselect_b32 s41, s41, s42
	s_add_i32 s30, s41, s51
	s_and_b64 s[4:5], s[4:5], exec
	v_lshrrev_b32_e32 v11, 4, v10
	s_cselect_b32 s42, s57, s18
	s_cselect_b32 s51, s56, s15
	s_ashr_i32 s31, s30, 31
	v_sub_u32_e32 v1, 0, v11
	s_lshl_b64 s[4:5], s[30:31], 11
	v_lshlrev_b32_e32 v0, 9, v10
	v_xor_b32_e32 v1, v10, v1
	s_add_u32 s30, s51, s4
	v_and_b32_e32 v0, 0x7800, v0
	v_lshlrev_b32_e32 v1, 4, v1
	s_addc_u32 s31, s42, s5
	s_lshl_b32 s4, s43, 12
	v_and_or_b32 v128, v1, 48, v0
	s_mov_b32 m0, s4
	v_lshl_add_u64 v[0:1], s[8:9], 0, v[128:129]
	global_load_lds_dwordx4 v128, s[8:9]
	s_or_b32 m0, s4, 0x400
	v_lshl_add_u64 v[2:3], s[10:11], 0, v[128:129]
	global_load_lds_dwordx4 v128, s[10:11]
	s_or_b32 m0, s4, 0x800
	v_lshl_add_u64 v[8:9], v[0:1], 0, 64
	global_load_lds_dwordx4 v128, s[28:29]
	s_or_b32 m0, s4, 0xc00
	v_lshl_add_u64 v[4:5], s[28:29], 0, v[128:129]
	global_load_lds_dwordx4 v128, s[30:31]
	s_add_i32 m0, s4, 0x8000
	v_lshl_add_u64 v[6:7], s[30:31], 0, v[128:129]
	global_load_lds_dwordx4 v[8:9], off
	v_lshl_add_u64 v[8:9], v[2:3], 0, 64
	s_add_i32 m0, s4, 0x8400
	v_lshl_add_u64 v[2:3], v[2:3], 0, s[88:89]
	global_load_lds_dwordx4 v[8:9], off
	v_lshl_add_u64 v[8:9], v[4:5], 0, 64
	s_add_i32 m0, s4, 0x8800
	s_lshr_b32 s5, s13, 1
	global_load_lds_dwordx4 v[8:9], off
	v_lshl_add_u64 v[8:9], v[6:7], 0, 64
	s_add_i32 m0, s4, 0x8c00
	s_add_i32 s8, s41, s44
	global_load_lds_dwordx4 v[8:9], off
	s_add_i32 m0, s4, 0x10000
	v_lshl_add_u64 v[8:9], v[0:1], 0, s[88:89]
	global_load_lds_dwordx4 v[8:9], off
	s_add_i32 m0, s4, 0x10400
	v_and_b32_e32 v12, 15, v10
	global_load_lds_dwordx4 v[2:3], off
	v_lshl_add_u64 v[2:3], v[4:5], 0, s[88:89]
	s_add_i32 m0, s4, 0x10800
	s_and_b32 s5, s5, 0x3ffff80
	global_load_lds_dwordx4 v[2:3], off
	v_lshl_add_u64 v[2:3], v[6:7], 0, s[88:89]
	s_add_i32 m0, s4, 0x10c00
	s_ashr_i32 s9, s8, 31
	global_load_lds_dwordx4 v[2:3], off
	v_lshrrev_b32_e32 v2, 2, v10
	v_sub_u32_e32 v2, 0, v2
	v_bitop3_b32 v2, v11, 3, v2 bitop3:0x48
	v_or_b32_e32 v3, s5, v12
	v_lshlrev_b32_e32 v2, 4, v2
	s_and_b32 s5, s13, 0xc0
	s_lshl_b64 s[8:9], s[8:9], 11
	v_lshl_or_b32 v141, v3, 6, v2
	v_or_b32_e32 v3, s5, v12
	s_add_u32 s8, s51, s8
	v_lshlrev_b32_e32 v3, 6, v3
	s_addc_u32 s9, s42, s9
	v_or3_b32 v142, v2, v3, s68
	v_lshl_add_u64 v[2:3], s[8:9], 0, v[128:129]
	s_add_i32 s8, s48, s44
	s_ashr_i32 s9, s8, 31
	s_lshl_b64 s[8:9], s[8:9], 11
	s_add_u32 s8, s50, s8
	s_addc_u32 s9, s49, s9
	v_lshl_add_u64 v[130:131], v[2:3], 0, s[92:93]
	v_lshl_add_u64 v[2:3], s[8:9], 0, v[128:129]
	s_add_i32 s8, s45, s44
	s_ashr_i32 s9, s8, 31
	s_lshl_b64 s[8:9], s[8:9], 11
	s_add_u32 s8, s47, s8
	s_addc_u32 s9, s46, s9
	v_lshl_add_u64 v[132:133], v[2:3], 0, s[94:95]
	v_lshl_add_u64 v[2:3], s[8:9], 0, v[128:129]
	v_lshl_add_u64 v[136:137], v[0:1], 0, s[78:79]
	v_mov_b32_e32 v0, 0
	v_lshl_add_u64 v[134:135], v[2:3], 0, s[96:97]
	s_mov_b32 s5, 0x18000
	v_mov_b32_e32 v1, v0
	v_mov_b32_e32 v2, v0
	v_mov_b32_e32 v3, v0
	v_mov_b32_e32 v4, v0
	v_mov_b32_e32 v5, v0
	v_mov_b32_e32 v6, v0
	v_mov_b32_e32 v7, v0
	v_mov_b32_e32 v8, v0
	v_mov_b32_e32 v9, v0
	v_mov_b32_e32 v10, v0
	v_mov_b32_e32 v11, v0
	v_mov_b32_e32 v12, v0
	v_mov_b32_e32 v13, v0
	v_mov_b32_e32 v14, v0
	v_mov_b32_e32 v15, v0
	v_mov_b32_e32 v16, v0
	v_mov_b32_e32 v17, v0
	v_mov_b32_e32 v18, v0
	v_mov_b32_e32 v19, v0
	v_mov_b32_e32 v20, v0
	v_mov_b32_e32 v21, v0
	v_mov_b32_e32 v22, v0
	v_mov_b32_e32 v23, v0
	v_mov_b32_e32 v24, v0
	v_mov_b32_e32 v25, v0
	v_mov_b32_e32 v26, v0
	v_mov_b32_e32 v27, v0
	v_mov_b32_e32 v28, v0
	v_mov_b32_e32 v29, v0
	v_mov_b32_e32 v30, v0
	v_mov_b32_e32 v31, v0
	v_mov_b32_e32 v32, v0
	v_mov_b32_e32 v33, v0
	v_mov_b32_e32 v34, v0
	v_mov_b32_e32 v35, v0
	v_mov_b32_e32 v36, v0
	v_mov_b32_e32 v37, v0
	v_mov_b32_e32 v38, v0
	v_mov_b32_e32 v39, v0
	v_mov_b32_e32 v40, v0
	v_mov_b32_e32 v41, v0
	v_mov_b32_e32 v42, v0
	v_mov_b32_e32 v43, v0
	v_mov_b32_e32 v44, v0
	v_mov_b32_e32 v45, v0
	v_mov_b32_e32 v46, v0
	v_mov_b32_e32 v47, v0
	v_mov_b32_e32 v48, v0
	v_mov_b32_e32 v49, v0
	v_mov_b32_e32 v50, v0
	v_mov_b32_e32 v51, v0
	v_mov_b32_e32 v52, v0
	v_mov_b32_e32 v53, v0
	v_mov_b32_e32 v54, v0
	v_mov_b32_e32 v55, v0
	v_mov_b32_e32 v56, v0
	v_mov_b32_e32 v57, v0
	v_mov_b32_e32 v58, v0
	v_mov_b32_e32 v59, v0
	v_mov_b32_e32 v60, v0
	v_mov_b32_e32 v61, v0
	v_mov_b32_e32 v62, v0
	v_mov_b32_e32 v63, v0
	v_mov_b32_e32 v64, v0
	v_mov_b32_e32 v65, v0
	v_mov_b32_e32 v66, v0
	v_mov_b32_e32 v67, v0
	v_mov_b32_e32 v68, v0
	v_mov_b32_e32 v69, v0
	v_mov_b32_e32 v70, v0
	v_mov_b32_e32 v71, v0
	v_mov_b32_e32 v72, v0
	v_mov_b32_e32 v73, v0
	v_mov_b32_e32 v74, v0
	v_mov_b32_e32 v75, v0
	v_mov_b32_e32 v76, v0
	v_mov_b32_e32 v77, v0
	v_mov_b32_e32 v78, v0
	v_mov_b32_e32 v79, v0
	v_mov_b32_e32 v80, v0
	v_mov_b32_e32 v81, v0
	v_mov_b32_e32 v82, v0
	v_mov_b32_e32 v83, v0
	v_mov_b32_e32 v84, v0
	v_mov_b32_e32 v85, v0
	v_mov_b32_e32 v86, v0
	v_mov_b32_e32 v87, v0
	v_mov_b32_e32 v88, v0
	v_mov_b32_e32 v89, v0
	v_mov_b32_e32 v90, v0
	v_mov_b32_e32 v91, v0
	v_mov_b32_e32 v92, v0
	v_mov_b32_e32 v93, v0
	v_mov_b32_e32 v94, v0
	v_mov_b32_e32 v95, v0
	v_mov_b32_e32 v96, v0
	v_mov_b32_e32 v97, v0
	v_mov_b32_e32 v98, v0
	v_mov_b32_e32 v99, v0
	v_mov_b32_e32 v100, v0
	v_mov_b32_e32 v101, v0
	v_mov_b32_e32 v102, v0
	v_mov_b32_e32 v103, v0
	v_mov_b32_e32 v104, v0
	v_mov_b32_e32 v105, v0
	v_mov_b32_e32 v106, v0
	v_mov_b32_e32 v107, v0
	v_mov_b32_e32 v108, v0
	v_mov_b32_e32 v109, v0
	v_mov_b32_e32 v110, v0
	v_mov_b32_e32 v111, v0
	v_mov_b32_e32 v112, v0
	v_mov_b32_e32 v113, v0
	v_mov_b32_e32 v114, v0
	v_mov_b32_e32 v115, v0
	v_mov_b32_e32 v116, v0
	v_mov_b32_e32 v117, v0
	v_mov_b32_e32 v118, v0
	v_mov_b32_e32 v119, v0
	v_mov_b32_e32 v120, v0
	v_mov_b32_e32 v121, v0
	v_mov_b32_e32 v122, v0
	v_mov_b32_e32 v123, v0
	v_mov_b32_e32 v124, v0
	v_mov_b32_e32 v125, v0
	v_mov_b32_e32 v126, v0
	v_mov_b32_e32 v127, v0
	s_add_i32 s8, s5, 0xfffe8000
	s_and_b32 s9, s5, 0x18000
	s_waitcnt vmcnt(8)
	s_barrier
	s_and_b32 s8, s8, 0x18000
	s_add_i32 s9, s4, s9
	v_add_u32_e32 v128, s8, v141
	v_or_b32_e32 v143, s8, v142
	s_add_i32 s11, s9, 0x400
	s_add_i32 s10, s9, 0x800
	s_add_i32 s8, s9, 0xc00
	s_add_i32 s5, s5, 0x8000
	s_cmp_eq_u32 s5, 0x100000
	ds_read_b128 v[174:177], v128
	ds_read_b128 v[144:147], v143
	ds_read_b128 v[158:161], v143 offset:1024
	ds_read_b128 v[162:165], v143 offset:2048
	ds_read_b128 v[166:169], v143 offset:3072
	ds_read_b128 v[178:181], v128 offset:1024
	ds_read_b128 v[182:185], v128 offset:2048
	ds_read_b128 v[186:189], v128 offset:3072
	ds_read_b128 v[232:235], v128 offset:4096
	ds_read_b128 v[236:239], v128 offset:5120
	ds_read_b128 v[240:243], v128 offset:6144
	ds_read_b128 v[244:247], v128 offset:7168
	s_mov_b32 m0, s9
	s_nop 0
	global_load_lds_dwordx4 v[136:137], off
	v_lshl_add_u64 v[136:137], v[136:137], 0, 64
	s_mov_b32 m0, s11
	s_nop 0
	global_load_lds_dwordx4 v[134:135], off
	v_lshl_add_u64 v[134:135], v[134:135], 0, 64
	s_mov_b32 m0, s10
	s_nop 0
	global_load_lds_dwordx4 v[132:133], off
	v_lshl_add_u64 v[132:133], v[132:133], 0, 64
	s_mov_b32 m0, s8
	s_nop 0
	global_load_lds_dwordx4 v[130:131], off
	v_lshl_add_u64 v[130:131], v[130:131], 0, 64
	s_waitcnt lgkmcnt(4)
	v_mfma_f32_16x16x32_bf16 v[124:127], v[174:177], v[144:147], v[124:127]
	v_mfma_f32_16x16x32_bf16 v[120:123], v[174:177], v[158:161], v[120:123]
	v_mfma_f32_16x16x32_bf16 v[116:119], v[174:177], v[162:165], v[116:119]
	v_mfma_f32_16x16x32_bf16 v[112:115], v[174:177], v[166:169], v[112:115]
	v_mfma_f32_16x16x32_bf16 v[108:111], v[178:181], v[144:147], v[108:111]
	v_mfma_f32_16x16x32_bf16 v[104:107], v[178:181], v[158:161], v[104:107]
	v_mfma_f32_16x16x32_bf16 v[100:103], v[178:181], v[162:165], v[100:103]
	v_mfma_f32_16x16x32_bf16 v[96:99], v[178:181], v[166:169], v[96:99]
	v_mfma_f32_16x16x32_bf16 v[92:95], v[182:185], v[144:147], v[92:95]
	v_mfma_f32_16x16x32_bf16 v[88:91], v[182:185], v[158:161], v[88:91]
	v_mfma_f32_16x16x32_bf16 v[84:87], v[182:185], v[162:165], v[84:87]
	v_mfma_f32_16x16x32_bf16 v[80:83], v[182:185], v[166:169], v[80:83]
	v_mfma_f32_16x16x32_bf16 v[76:79], v[186:189], v[144:147], v[76:79]
	v_mfma_f32_16x16x32_bf16 v[72:75], v[186:189], v[158:161], v[72:75]
	v_mfma_f32_16x16x32_bf16 v[68:71], v[186:189], v[162:165], v[68:71]
	v_mfma_f32_16x16x32_bf16 v[64:67], v[186:189], v[166:169], v[64:67]
